# hand-written lru_gates: conv loads batched per k-slab, branch-free gate math (cndmask), double-buffered gate-weight loads
# speedup vs baseline: 1.0653x; 1.0082x over previous
; template <int NV, bool FIRST>
; DI void conv_vec(float (&x)[NV], const bf16_t* XB, const float* cw, const float* cb, const float* cbuf, int row, int pos, int c) {
; #pragma unroll
;     for (int e4 = 0; e4 < NV / 4; ++e4) { const f32x4 b4 = *(const f32x4*)(cb + c + 4 * e4);
; #pragma unroll
;         for (int e = 0; e < 4; ++e) x[4 * e4 + e] = b4[e]; }
; #pragma unroll
;     for (int k = 0; k < 4; ++k) { const int i = pos + k; float v[NV];
;         if (!FIRST || i >= 3) { const bf16_t* src = XB + (size_t)(row - 3 + k) * DRNN + c;
;             if (NV == 8) { const u32x4 q = *(const u32x4*)src; v[0] = bflo(q.x); v[1] = bfhi(q.x); v[2] = bflo(q.y); v[3] = bfhi(q.y); v[4 % NV] = bflo(q.z); v[5 % NV] = bfhi(q.z); v[6 % NV] = bflo(q.w); v[7 % NV] = bfhi(q.w); }
;             else { const u32x2 q = *(const u32x2*)src; v[0] = bflo(q.x); v[1] = bfhi(q.x); v[2] = bflo(q.y); v[3] = bfhi(q.y); }
;         } else if (cbuf) {
; #pragma unroll
;             for (int e4 = 0; e4 < NV / 4; ++e4) { const f32x4 a4 = *(const f32x4*)(cbuf + (size_t)i * DRNN + c + 4 * e4);
; #pragma unroll
;                 for (int e = 0; e < 4; ++e) v[4 * e4 + e] = a4[e]; }
;         } else {
; #pragma unroll
; DI void phase_lru_gates(const Frame& F, int j) {
;     LruP P;
;     P.WG = (const bf16_t*)(F.ws + WS_WG) + (size_t)j * 16 * 160 * 96; P.XB = (const bf16_t*)(F.ws + WS_XB);
;     P.A = (float*)(F.ws + WS_A); P.Bn = (float*)(F.ws + WS_BN);
;     P.cw = F.in[15] + (size_t)j * 4 * DRNN; P.cb = F.in[16] + (size_t)j * DRNN;
;     P.gab = F.in[18] + (size_t)j * DRNN; P.gxb = F.in[20] + (size_t)j * DRNN; P.spl = (const float*)(F.ws + WS_SPL) + (size_t)j * DRNN;
;     const float* cst = F.in[5];
;     const int fr = F.lane & 15, fq = F.lane >> 4;
;     LAS float* xcs = (LAS float*)(F.lds + F.wave * 16384);
; #pragma unroll 1
;     for (int task = F.gw; task < (NT / 32) * 16; task += F.NGW) {
;         asm volatile("" ::: "memory");
;         const int hb = task & 15, tp = task >> 4; const int row = tp * 32 + fr; const int seq = seq_of_row(row), pos = pos_of_row(row);
;         const bool first = pos_of_row(tp * 32) == 0;
;         if (first) { const float* cbuf = row < NP ? nullptr : cst + ((size_t)j * 8 + (seq - 2)) * 3 * DRNN; lru_tile2<true>(P, cbuf, hb, row, pos, fr, fq, xcs); }
;         else lru_tile2<false>(P, nullptr, hb, row, pos, fr, fq, xcs);
.LBB0_1159:
	s_or_b64 exec, exec, s[0:1]
	v_mov_b32_e32 v2, v220
	s_waitcnt lgkmcnt(0)
	s_barrier
	v_mov_b32_e32 v102, 0x23110
	ds_read_b64 v[2:3], v102
	v_mov_b32_e32 v102, 0x23078
	ds_read_b64 v[4:5], v102
	v_mov_b32_e32 v102, 0x23080
	ds_read_b64 v[6:7], v102
	v_mov_b32_e32 v102, 0x23090
	ds_read_b64 v[8:9], v102
	v_mov_b32_e32 v102, 0x230a0
	ds_read_b64 v[22:23], v102
	v_mov_b32_e32 v102, 0x23028
	ds_read_b64 v[24:25], v102
	v_and_b32_e32 v103, 63, v220
	v_and_b32_e32 v1, 15, v103
	v_lshrrev_b32_e32 v10, 4, v103
	v_readlane_b32 s41, v255, 24
	s_lshr_b32 s41, s41, 1
	v_readfirstlane_b32 s66, v220
	s_lshr_b32 s66, s66, 6
	v_readlane_b32 s2, v253, 2
	s_add_i32 s2, s2, s66
	s_mov_b32 s71, 0xffff0000
	s_waitcnt lgkmcnt(0)
	v_readfirstlane_b32 s42, v2
	v_readfirstlane_b32 s43, v3
	v_readfirstlane_b32 s84, v4
	v_readfirstlane_b32 s85, v5
	v_readfirstlane_b32 s88, v6
	v_readfirstlane_b32 s89, v7
	v_readfirstlane_b32 s92, v8
	v_readfirstlane_b32 s93, v9
	v_readfirstlane_b32 s96, v22
	v_readfirstlane_b32 s97, v23
	v_readfirstlane_b32 s22, v24
	v_readfirstlane_b32 s23, v25
	s_mul_i32 s75, s41, 0x5000
	s_add_u32 s84, s84, s75
	s_addc_u32 s85, s85, 0
	s_mul_i32 s75, s41, 0x1400
	s_add_u32 s88, s88, s75
	s_addc_u32 s89, s89, 0
	s_add_u32 s92, s92, s75
	s_addc_u32 s93, s93, 0
	s_add_u32 s96, s96, s75
	s_addc_u32 s97, s97, 0
	s_add_i32 s75, s75, 0x80000
	s_add_u32 s98, s42, s75
	s_addc_u32 s99, s43, 0
	s_mul_i32 s75, s41, 0x1e000
	s_add_u32 s22, s22, s75
	s_addc_u32 s23, s23, 0
	s_mul_i32 s75, s41, 0x78000
	s_add_i32 s75, s75, 0x300000
	s_add_u32 s48, s42, s75
	s_addc_u32 s49, s43, 0
	v_add_u32_e32 v11, 0, v1
	v_mul_u32_u24_e32 v11, 0xa00, v11
	v_lshl_add_u32 v11, v10, 4, v11
	v_add_u32_e32 v12, 1, v1
	v_mul_u32_u24_e32 v12, 0xa00, v12
	v_lshl_add_u32 v12, v10, 4, v12
	v_add_u32_e32 v14, 2, v1
	v_mul_u32_u24_e32 v14, 0xa00, v14
	v_lshl_add_u32 v14, v10, 4, v14
	v_add_u32_e32 v15, 3, v1
	v_mul_u32_u24_e32 v15, 0xa00, v15
	v_lshl_add_u32 v15, v10, 4, v15
	v_mul_u32_u24_e32 v94, 0xc0, v1
	v_lshl_add_u32 v94, v10, 4, v94
	v_add_u32_e32 v96, 0x3c00, v94
	v_mul_u32_u24_e32 v129, 0x1400, v1
	v_lshl_add_u32 v129, v10, 4, v129
	v_add_u32_e32 v130, 0x14000, v129
	s_lshl_b32 s75, s66, 14
	v_mul_u32_u24_e32 v237, 0x150, v1
	v_add_u32_e32 v237, s75, v237
	v_lshl_add_u32 v131, v10, 5, v237
	v_lshl_add_u32 v237, v10, 4, v237
.Llg_task:
	s_cmp_ge_u32 s2, 0x2080
	s_cbranch_scc1 .Llg_done
	s_and_b32 s15, s2, 15
	s_lshr_b32 s24, s2, 4
	s_lshl_b32 s24, s24, 5
	s_and_b32 s32, s24, 0x1fff
	s_cmp_eq_u32 s32, 0
	s_cselect_b32 s32, 1, 0
	s_cmp_ge_u32 s24, 0x4000
	s_cselect_b32 s32, 1, s32
	s_mul_i32 s75, s15, 0x140
	v_lshl_add_u32 v16, v10, 5, s75
	v_lshl_add_u32 v18, v10, 5, s75
	v_add_u32_e32 v18, 5120, v18
	v_lshl_add_u32 v54, v10, 5, s75
	v_add_u32_e32 v54, 10240, v54
	v_lshl_add_u32 v55, v10, 5, s75
	v_add_u32_e32 v55, 15360, v55
	v_lshl_add_u32 v56, v10, 5, s75
	v_lshl_add_u32 v128, v10, 4, s75
	s_sub_i32 s75, s24, 3
	s_mul_i32 s75, s75, 0xa00
	s_mul_i32 s90, s15, 0xa0
	s_add_i32 s75, s75, s90
	s_add_i32 s75, s75, 0x13000000
	s_ashr_i32 s90, s75, 31
	s_add_u32 s44, s42, s75
	s_addc_u32 s45, s43, s90
	s_add_u32 s46, s44, 0xa000
	s_addc_u32 s47, s45, 0
	s_mul_i32 s75, s24, 0x1400
	s_mul_i32 s90, s15, 0x140
	s_add_i32 s75, s75, s90
	s_add_u32 s78, s42, s75
	s_addc_u32 s79, s43, 0
	s_add_u32 s78, s78, 0x16000000
	s_addc_u32 s79, s79, 0
	s_mul_i32 s75, s15, 0x7800
	s_add_u32 s68, s48, s75
	s_addc_u32 s69, s49, 0
	v_mov_b32_e32 v22, 0
	v_mov_b32_e32 v23, 0
	v_mov_b32_e32 v24, 0
	v_mov_b32_e32 v25, 0
	v_mov_b32_e32 v38, 0
	v_mov_b32_e32 v39, 0
	v_mov_b32_e32 v40, 0
	v_mov_b32_e32 v41, 0
	global_load_dwordx4 v[180:183], v16, s[84:85] offset:0
	global_load_dwordx4 v[184:187], v16, s[84:85] offset:16
	global_load_dwordx4 v[188:191], v18, s[84:85] offset:0
	global_load_dwordx4 v[192:195], v18, s[84:85] offset:16
	global_load_dwordx4 v[196:199], v54, s[84:85] offset:0
	global_load_dwordx4 v[200:203], v54, s[84:85] offset:16
	global_load_dwordx4 v[204:207], v55, s[84:85] offset:0
	global_load_dwordx4 v[208:211], v55, s[84:85] offset:16
	global_load_dwordx4 v[212:215], v56, s[88:89] offset:0
	global_load_dwordx4 v[238:241], v56, s[88:89] offset:16
	global_load_dwordx4 v[140:143], v11, s[44:45] offset:0
	global_load_dwordx4 v[144:147], v12, s[44:45] offset:0
	global_load_dwordx4 v[148:151], v14, s[44:45] offset:0
	global_load_dwordx4 v[152:155], v15, s[44:45] offset:0
	global_load_dwordx4 v[156:159], v11, s[46:47] offset:0
	global_load_dwordx4 v[160:163], v12, s[46:47] offset:0
	global_load_dwordx4 v[164:167], v14, s[46:47] offset:0
	global_load_dwordx4 v[168:171], v15, s[46:47] offset:0
	s_cmp_eq_u32 s32, 0
	s_cbranch_scc1 .Llg_nf0
	v_mov_b32_e32 v62, 0
	v_mov_b32_e32 v63, 0
	v_mov_b32_e32 v64, 0
	v_mov_b32_e32 v65, 0
	v_mov_b32_e32 v78, 0
	v_mov_b32_e32 v79, 0
	v_mov_b32_e32 v80, 0
	v_mov_b32_e32 v81, 0
	v_mov_b32_e32 v82, 0
	v_mov_b32_e32 v83, 0
	v_mov_b32_e32 v84, 0
	v_mov_b32_e32 v85, 0
	v_mov_b32_e32 v86, 0
	v_mov_b32_e32 v87, 0
	v_mov_b32_e32 v88, 0
	v_mov_b32_e32 v89, 0
	v_mov_b32_e32 v90, 0
	v_mov_b32_e32 v91, 0
	v_mov_b32_e32 v92, 0
	v_mov_b32_e32 v93, 0
	v_mov_b32_e32 v98, 0
	v_mov_b32_e32 v99, 0
	v_mov_b32_e32 v100, 0
	v_mov_b32_e32 v101, 0
	s_cmp_lt_u32 s24, 0x4000
	s_cbranch_scc1 .Llg_st0
	s_sub_i32 s75, s24, 0x4000
	s_lshr_b32 s75, s75, 5
	s_mul_i32 s75, s75, 0x3c00
	s_add_u32 s0, s22, s75
	s_addc_u32 s1, s23, 0
	v_add_u32_e32 v104, 0, v1
	v_min_u32_e32 v104, 2, v104
	v_mul_u32_u24_e32 v104, 0x1400, v104
	v_add_u32_e32 v216, v104, v56
	global_load_dwordx4 v[62:65], v216, s[0:1] offset:0
	global_load_dwordx4 v[78:81], v216, s[0:1] offset:16
	v_add_u32_e32 v104, 1, v1
	v_min_u32_e32 v104, 2, v104
	v_mul_u32_u24_e32 v104, 0x1400, v104
	v_add_u32_e32 v217, v104, v56
	global_load_dwordx4 v[82:85], v217, s[0:1] offset:0
	global_load_dwordx4 v[86:89], v217, s[0:1] offset:16
	v_add_u32_e32 v104, 2, v1
	v_min_u32_e32 v104, 2, v104
	v_mul_u32_u24_e32 v104, 0x1400, v104
	v_add_u32_e32 v218, v104, v56
	global_load_dwordx4 v[90:93], v218, s[0:1] offset:0
	global_load_dwordx4 v[98:101], v218, s[0:1] offset:16
; DI float bflo(unsigned w) { return __uint_as_float(w << 16); }
; DI float bfhi(unsigned w) { return __uint_as_float(w & 0xffff0000u); }
; template <int NV, bool FIRST>
; DI void conv_vec(float (&x)[NV], const bf16_t* XB, const float* cw, const float* cb, const float* cbuf, int row, int pos, int c) {
; #pragma unroll
;     for (int e4 = 0; e4 < NV / 4; ++e4) { const f32x4 b4 = *(const f32x4*)(cb + c + 4 * e4);
; #pragma unroll
;         for (int e = 0; e < 4; ++e) x[4 * e4 + e] = b4[e]; }
; #pragma unroll
;     for (int k = 0; k < 4; ++k) { const int i = pos + k; float v[NV];
;         if (!FIRST || i >= 3) { const bf16_t* src = XB + (size_t)(row - 3 + k) * DRNN + c;
;             if (NV == 8) { const u32x4 q = *(const u32x4*)src; v[0] = bflo(q.x); v[1] = bfhi(q.x); v[2] = bflo(q.y); v[3] = bfhi(q.y); v[4 % NV] = bflo(q.z); v[5 % NV] = bfhi(q.z); v[6 % NV] = bflo(q.w); v[7 % NV] = bfhi(q.w); }
;             else { const u32x2 q = *(const u32x2*)src; v[0] = bflo(q.x); v[1] = bfhi(q.x); v[2] = bflo(q.y); v[3] = bfhi(q.y); }
;         } else if (cbuf) {
; #pragma unroll
;             for (int e4 = 0; e4 < NV / 4; ++e4) { const f32x4 a4 = *(const f32x4*)(cbuf + (size_t)i * DRNN + c + 4 * e4);
; #pragma unroll
;                 for (int e = 0; e < 4; ++e) v[4 * e4 + e] = a4[e]; }
;         } else {
; #pragma unroll
;             for (int e = 0; e < NV; ++e) v[e] = 0.f;
;         }
; #pragma unroll
;         for (int e4 = 0; e4 < NV / 4; ++e4) { const f32x4 w4 = *(const f32x4*)(cw + k * DRNN + c + 4 * e4);
; #pragma unroll
;             for (int e = 0; e < 4; ++e) x[4 * e4 + e] += w4[e] * v[4 * e4 + e]; } }
.Llg_st0:
	s_waitcnt vmcnt(0)
	v_mov_b32_e32 v42, v212
	v_mov_b32_e32 v43, v213
	v_mov_b32_e32 v44, v214
	v_mov_b32_e32 v45, v215
	v_mov_b32_e32 v46, v238
	v_mov_b32_e32 v47, v239
	v_mov_b32_e32 v48, v240
	v_mov_b32_e32 v49, v241
	v_add_u32_e32 v104, 0, v1
	v_cmp_gt_u32_e32 vcc, 3, v104
	v_lshlrev_b32_e32 v102, 16, v140
	v_and_b32_e32 v103, s71, v140
	v_cndmask_b32_e32 v102, v102, v62, vcc
	v_cndmask_b32_e32 v103, v103, v63, vcc
	v_fmac_f32_e32 v42, v180, v102
	v_fmac_f32_e32 v43, v181, v103
	v_lshlrev_b32_e32 v102, 16, v141
	v_and_b32_e32 v103, s71, v141
	v_cndmask_b32_e32 v102, v102, v64, vcc
	v_cndmask_b32_e32 v103, v103, v65, vcc
	v_fmac_f32_e32 v44, v182, v102
	v_fmac_f32_e32 v45, v183, v103
	v_lshlrev_b32_e32 v102, 16, v142
	v_and_b32_e32 v103, s71, v142
	v_cndmask_b32_e32 v102, v102, v78, vcc
	v_cndmask_b32_e32 v103, v103, v79, vcc
	v_fmac_f32_e32 v46, v184, v102
	v_fmac_f32_e32 v47, v185, v103
	v_lshlrev_b32_e32 v102, 16, v143
	v_and_b32_e32 v103, s71, v143
	v_cndmask_b32_e32 v102, v102, v80, vcc
	v_cndmask_b32_e32 v103, v103, v81, vcc
	v_fmac_f32_e32 v48, v186, v102
	v_fmac_f32_e32 v49, v187, v103
	v_add_u32_e32 v104, 1, v1
	v_cmp_gt_u32_e32 vcc, 3, v104
	v_lshlrev_b32_e32 v102, 16, v144
	v_and_b32_e32 v103, s71, v144
	v_cndmask_b32_e32 v102, v102, v82, vcc
	v_cndmask_b32_e32 v103, v103, v83, vcc
	v_fmac_f32_e32 v42, v188, v102
	v_fmac_f32_e32 v43, v189, v103
	v_lshlrev_b32_e32 v102, 16, v145
	v_and_b32_e32 v103, s71, v145
	v_cndmask_b32_e32 v102, v102, v84, vcc
	v_cndmask_b32_e32 v103, v103, v85, vcc
	v_fmac_f32_e32 v44, v190, v102
	v_fmac_f32_e32 v45, v191, v103
	v_lshlrev_b32_e32 v102, 16, v146
	v_and_b32_e32 v103, s71, v146
	v_cndmask_b32_e32 v102, v102, v86, vcc
	v_cndmask_b32_e32 v103, v103, v87, vcc
	v_fmac_f32_e32 v46, v192, v102
	v_fmac_f32_e32 v47, v193, v103
	v_lshlrev_b32_e32 v102, 16, v147
	v_and_b32_e32 v103, s71, v147
	v_cndmask_b32_e32 v102, v102, v88, vcc
	v_cndmask_b32_e32 v103, v103, v89, vcc
	v_fmac_f32_e32 v48, v194, v102
	v_fmac_f32_e32 v49, v195, v103
	v_add_u32_e32 v104, 2, v1
	v_cmp_gt_u32_e32 vcc, 3, v104
	v_lshlrev_b32_e32 v102, 16, v148
	v_and_b32_e32 v103, s71, v148
	v_cndmask_b32_e32 v102, v102, v90, vcc
	v_cndmask_b32_e32 v103, v103, v91, vcc
	v_fmac_f32_e32 v42, v196, v102
	v_fmac_f32_e32 v43, v197, v103
	v_lshlrev_b32_e32 v102, 16, v149
	v_and_b32_e32 v103, s71, v149
	v_cndmask_b32_e32 v102, v102, v92, vcc
	v_cndmask_b32_e32 v103, v103, v93, vcc
	v_fmac_f32_e32 v44, v198, v102
	v_fmac_f32_e32 v45, v199, v103
	v_lshlrev_b32_e32 v102, 16, v150
	v_and_b32_e32 v103, s71, v150
	v_cndmask_b32_e32 v102, v102, v98, vcc
	v_cndmask_b32_e32 v103, v103, v99, vcc
	v_fmac_f32_e32 v46, v200, v102
	v_fmac_f32_e32 v47, v201, v103
	v_lshlrev_b32_e32 v102, 16, v151
	v_and_b32_e32 v103, s71, v151
	v_cndmask_b32_e32 v102, v102, v100, vcc
	v_cndmask_b32_e32 v103, v103, v101, vcc
	v_fmac_f32_e32 v48, v202, v102
	v_fmac_f32_e32 v49, v203, v103
	v_lshlrev_b32_e32 v102, 16, v152
	v_and_b32_e32 v103, s71, v152
	v_fmac_f32_e32 v42, v204, v102
	v_fmac_f32_e32 v43, v205, v103
	v_lshlrev_b32_e32 v102, 16, v153
	v_and_b32_e32 v103, s71, v153
	v_fmac_f32_e32 v44, v206, v102
	v_fmac_f32_e32 v45, v207, v103
	v_lshlrev_b32_e32 v102, 16, v154
	v_and_b32_e32 v103, s71, v154
	v_fmac_f32_e32 v46, v208, v102
	v_fmac_f32_e32 v47, v209, v103
	v_lshlrev_b32_e32 v102, 16, v155
	v_and_b32_e32 v103, s71, v155
	v_fmac_f32_e32 v48, v210, v102
	v_fmac_f32_e32 v49, v211, v103
	s_branch .Llg_j0
.Llg_nf0:
	s_waitcnt vmcnt(0)
	v_mov_b32_e32 v42, v212
	v_mov_b32_e32 v43, v213
	v_mov_b32_e32 v44, v214
	v_mov_b32_e32 v45, v215
	v_mov_b32_e32 v46, v238
	v_mov_b32_e32 v47, v239
	v_mov_b32_e32 v48, v240
	v_mov_b32_e32 v49, v241
	v_lshlrev_b32_e32 v102, 16, v140
	v_and_b32_e32 v103, s71, v140
	v_fmac_f32_e32 v42, v180, v102
	v_fmac_f32_e32 v43, v181, v103
	v_lshlrev_b32_e32 v102, 16, v141
	v_and_b32_e32 v103, s71, v141
	v_fmac_f32_e32 v44, v182, v102
	v_fmac_f32_e32 v45, v183, v103
	v_lshlrev_b32_e32 v102, 16, v142
	v_and_b32_e32 v103, s71, v142
	v_fmac_f32_e32 v46, v184, v102
	v_fmac_f32_e32 v47, v185, v103
	v_lshlrev_b32_e32 v102, 16, v143
	v_and_b32_e32 v103, s71, v143
	v_fmac_f32_e32 v48, v186, v102
	v_fmac_f32_e32 v49, v187, v103
	v_lshlrev_b32_e32 v102, 16, v144
	v_and_b32_e32 v103, s71, v144
	v_fmac_f32_e32 v42, v188, v102
	v_fmac_f32_e32 v43, v189, v103
	v_lshlrev_b32_e32 v102, 16, v145
	v_and_b32_e32 v103, s71, v145
	v_fmac_f32_e32 v44, v190, v102
	v_fmac_f32_e32 v45, v191, v103
	v_lshlrev_b32_e32 v102, 16, v146
	v_and_b32_e32 v103, s71, v146
	v_fmac_f32_e32 v46, v192, v102
	v_fmac_f32_e32 v47, v193, v103
	v_lshlrev_b32_e32 v102, 16, v147
	v_and_b32_e32 v103, s71, v147
	v_fmac_f32_e32 v48, v194, v102
	v_fmac_f32_e32 v49, v195, v103
	v_lshlrev_b32_e32 v102, 16, v148
	v_and_b32_e32 v103, s71, v148
	v_fmac_f32_e32 v42, v196, v102
	v_fmac_f32_e32 v43, v197, v103
	v_lshlrev_b32_e32 v102, 16, v149
	v_and_b32_e32 v103, s71, v149
	v_fmac_f32_e32 v44, v198, v102
	v_fmac_f32_e32 v45, v199, v103
	v_lshlrev_b32_e32 v102, 16, v150
	v_and_b32_e32 v103, s71, v150
	v_fmac_f32_e32 v46, v200, v102
	v_fmac_f32_e32 v47, v201, v103
	v_lshlrev_b32_e32 v102, 16, v151
	v_and_b32_e32 v103, s71, v151
	v_fmac_f32_e32 v48, v202, v102
	v_fmac_f32_e32 v49, v203, v103
	v_lshlrev_b32_e32 v102, 16, v152
	v_and_b32_e32 v103, s71, v152
	v_fmac_f32_e32 v42, v204, v102
	v_fmac_f32_e32 v43, v205, v103
	v_lshlrev_b32_e32 v102, 16, v153
	v_and_b32_e32 v103, s71, v153
	v_fmac_f32_e32 v44, v206, v102
	v_fmac_f32_e32 v45, v207, v103
	v_lshlrev_b32_e32 v102, 16, v154
	v_and_b32_e32 v103, s71, v154
	v_fmac_f32_e32 v46, v208, v102
	v_fmac_f32_e32 v47, v209, v103
	v_lshlrev_b32_e32 v102, 16, v155
	v_and_b32_e32 v103, s71, v155
	v_fmac_f32_e32 v48, v210, v102
	v_fmac_f32_e32 v49, v211, v103
; #define LAS __attribute__((address_space(3)))
; template <int NV, bool FIRST>
; DI void conv_vec(float (&x)[NV], const bf16_t* XB, const float* cw, const float* cb, const float* cbuf, int row, int pos, int c) {
; #pragma unroll
;     for (int e4 = 0; e4 < NV / 4; ++e4) { const f32x4 b4 = *(const f32x4*)(cb + c + 4 * e4);
; #pragma unroll
;         for (int e = 0; e < 4; ++e) x[4 * e4 + e] = b4[e]; }
; #pragma unroll
;     for (int k = 0; k < 4; ++k) { const int i = pos + k; float v[NV];
;         if (!FIRST || i >= 3) { const bf16_t* src = XB + (size_t)(row - 3 + k) * DRNN + c;
;             if (NV == 8) { const u32x4 q = *(const u32x4*)src; v[0] = bflo(q.x); v[1] = bfhi(q.x); v[2] = bflo(q.y); v[3] = bfhi(q.y); v[4 % NV] = bflo(q.z); v[5 % NV] = bfhi(q.z); v[6 % NV] = bflo(q.w); v[7 % NV] = bfhi(q.w); }
;             else { const u32x2 q = *(const u32x2*)src; v[0] = bflo(q.x); v[1] = bfhi(q.x); v[2] = bflo(q.y); v[3] = bfhi(q.y); }
;         } else if (cbuf) {
; #pragma unroll
;             for (int e4 = 0; e4 < NV / 4; ++e4) { const f32x4 a4 = *(const f32x4*)(cbuf + (size_t)i * DRNN + c + 4 * e4);
; #pragma unroll
;                 for (int e = 0; e < 4; ++e) v[4 * e4 + e] = a4[e]; }
;         } else {
; #pragma unroll
;             for (int e = 0; e < NV; ++e) v[e] = 0.f;
;         }
; #pragma unroll
;         for (int e4 = 0; e4 < NV / 4; ++e4) { const f32x4 w4 = *(const f32x4*)(cw + k * DRNN + c + 4 * e4);
; #pragma unroll
;             for (int e = 0; e < 4; ++e) x[4 * e4 + e] += w4[e] * v[4 * e4 + e]; } }
; }
; template <bool FIRST>
; DI void lru_tile2(const LruP& P, const float* cbuf, int hb, int row, int pos, int fr, int fq, LAS float* xcs) {
;     bf16x8 W[2][6]; f32x4 C[2][3];
;     ...
;     LRU_PRELOAD(0, 0);
;     bf16x8 xf[2][3];
; #pragma unroll
;     for (int tl = 0; tl < 2; ++tl)
; #pragma unroll
;         for (int ks = 0; ks < 3; ++ks) { const int kc = 32 * ks + 8 * fq; u32x4 w = (u32x4){0u, 0u, 0u, 0u};
;             if (kc < 80) { float x[8];
;                 if (tl == 0) conv_vec<8, FIRST>(x, P.XB, P.cw, P.cb, cbuf, row, pos, 80 * hb + kc); else conv_vec<8, false>(x, P.XB, P.cw, P.cb, nullptr, row + 16, pos + 16, 80 * hb + kc);
;                 w.x = cvt_pk_bf16(x[0], x[1]); w.y = cvt_pk_bf16(x[2], x[3]); w.z = cvt_pk_bf16(x[4], x[5]); w.w = cvt_pk_bf16(x[6], x[7]);
;                 LAS float* xp = xcs + (tl * 16 + fr) * XCP + kc;
.Llg_j0:
	v_mov_b32_e32 v50, v212
	v_mov_b32_e32 v51, v213
	v_mov_b32_e32 v52, v214
	v_mov_b32_e32 v53, v215
	v_mov_b32_e32 v58, v238
	v_mov_b32_e32 v59, v239
	v_mov_b32_e32 v60, v240
	v_mov_b32_e32 v61, v241
	v_lshlrev_b32_e32 v102, 16, v156
	v_and_b32_e32 v103, s71, v156
	v_fmac_f32_e32 v50, v180, v102
	v_fmac_f32_e32 v51, v181, v103
	v_lshlrev_b32_e32 v102, 16, v157
	v_and_b32_e32 v103, s71, v157
	v_fmac_f32_e32 v52, v182, v102
	v_fmac_f32_e32 v53, v183, v103
	v_lshlrev_b32_e32 v102, 16, v158
	v_and_b32_e32 v103, s71, v158
	v_fmac_f32_e32 v58, v184, v102
	v_fmac_f32_e32 v59, v185, v103
	v_lshlrev_b32_e32 v102, 16, v159
	v_and_b32_e32 v103, s71, v159
	v_fmac_f32_e32 v60, v186, v102
	v_fmac_f32_e32 v61, v187, v103
	v_lshlrev_b32_e32 v102, 16, v160
	v_and_b32_e32 v103, s71, v160
	v_fmac_f32_e32 v50, v188, v102
	v_fmac_f32_e32 v51, v189, v103
	v_lshlrev_b32_e32 v102, 16, v161
	v_and_b32_e32 v103, s71, v161
	v_fmac_f32_e32 v52, v190, v102
	v_fmac_f32_e32 v53, v191, v103
	v_lshlrev_b32_e32 v102, 16, v162
	v_and_b32_e32 v103, s71, v162
	v_fmac_f32_e32 v58, v192, v102
	v_fmac_f32_e32 v59, v193, v103
	v_lshlrev_b32_e32 v102, 16, v163
	v_and_b32_e32 v103, s71, v163
	v_fmac_f32_e32 v60, v194, v102
	v_fmac_f32_e32 v61, v195, v103
	v_lshlrev_b32_e32 v102, 16, v164
	v_and_b32_e32 v103, s71, v164
	v_fmac_f32_e32 v50, v196, v102
	v_fmac_f32_e32 v51, v197, v103
	v_lshlrev_b32_e32 v102, 16, v165
	v_and_b32_e32 v103, s71, v165
	v_fmac_f32_e32 v52, v198, v102
	v_fmac_f32_e32 v53, v199, v103
	v_lshlrev_b32_e32 v102, 16, v166
	v_and_b32_e32 v103, s71, v166
	v_fmac_f32_e32 v58, v200, v102
	v_fmac_f32_e32 v59, v201, v103
	v_lshlrev_b32_e32 v102, 16, v167
	v_and_b32_e32 v103, s71, v167
	v_fmac_f32_e32 v60, v202, v102
	v_fmac_f32_e32 v61, v203, v103
	v_lshlrev_b32_e32 v102, 16, v168
	v_and_b32_e32 v103, s71, v168
	v_fmac_f32_e32 v50, v204, v102
	v_fmac_f32_e32 v51, v205, v103
	v_lshlrev_b32_e32 v102, 16, v169
	v_and_b32_e32 v103, s71, v169
	v_fmac_f32_e32 v52, v206, v102
	v_fmac_f32_e32 v53, v207, v103
	v_lshlrev_b32_e32 v102, 16, v170
	v_and_b32_e32 v103, s71, v170
	v_fmac_f32_e32 v58, v208, v102
	v_fmac_f32_e32 v59, v209, v103
	v_lshlrev_b32_e32 v102, 16, v171
	v_and_b32_e32 v103, s71, v171
	v_fmac_f32_e32 v60, v210, v102
	v_fmac_f32_e32 v61, v211, v103
	v_cvt_pk_bf16_f32 v2, v42, v43
	v_cvt_pk_bf16_f32 v3, v44, v45
	v_cvt_pk_bf16_f32 v4, v46, v47
	v_cvt_pk_bf16_f32 v5, v48, v49
	ds_write_b128 v131, v[42:45] offset:0
	ds_write_b128 v131, v[46:49] offset:16
	v_cvt_pk_bf16_f32 v30, v50, v51
	v_cvt_pk_bf16_f32 v31, v52, v53
	v_cvt_pk_bf16_f32 v32, v58, v59
	v_cvt_pk_bf16_f32 v33, v60, v61
	ds_write_b128 v131, v[50:53] offset:5376
	ds_write_b128 v131, v[58:61] offset:5392
	global_load_dwordx4 v[180:183], v16, s[84:85] offset:128
	global_load_dwordx4 v[184:187], v16, s[84:85] offset:144
	global_load_dwordx4 v[188:191], v18, s[84:85] offset:128
	global_load_dwordx4 v[192:195], v18, s[84:85] offset:144
	global_load_dwordx4 v[196:199], v54, s[84:85] offset:128
	global_load_dwordx4 v[200:203], v54, s[84:85] offset:144
	global_load_dwordx4 v[204:207], v55, s[84:85] offset:128
	global_load_dwordx4 v[208:211], v55, s[84:85] offset:144
	global_load_dwordx4 v[212:215], v56, s[88:89] offset:128
	global_load_dwordx4 v[238:241], v56, s[88:89] offset:144
	global_load_dwordx4 v[140:143], v11, s[44:45] offset:64
	global_load_dwordx4 v[144:147], v12, s[44:45] offset:64
	global_load_dwordx4 v[148:151], v14, s[44:45] offset:64
	global_load_dwordx4 v[152:155], v15, s[44:45] offset:64
	global_load_dwordx4 v[156:159], v11, s[46:47] offset:64
	global_load_dwordx4 v[160:163], v12, s[46:47] offset:64
	global_load_dwordx4 v[164:167], v14, s[46:47] offset:64
	global_load_dwordx4 v[168:171], v15, s[46:47] offset:64
	s_cmp_eq_u32 s32, 0
	s_cbranch_scc1 .Llg_nf1
	v_mov_b32_e32 v62, 0
	v_mov_b32_e32 v63, 0
	v_mov_b32_e32 v64, 0
	v_mov_b32_e32 v65, 0
	v_mov_b32_e32 v78, 0
	v_mov_b32_e32 v79, 0
	v_mov_b32_e32 v80, 0
	v_mov_b32_e32 v81, 0
	v_mov_b32_e32 v82, 0
	v_mov_b32_e32 v83, 0
	v_mov_b32_e32 v84, 0
	v_mov_b32_e32 v85, 0
	v_mov_b32_e32 v86, 0
	v_mov_b32_e32 v87, 0
	v_mov_b32_e32 v88, 0
	v_mov_b32_e32 v89, 0
	v_mov_b32_e32 v90, 0
	v_mov_b32_e32 v91, 0
	v_mov_b32_e32 v92, 0
	v_mov_b32_e32 v93, 0
	v_mov_b32_e32 v98, 0
	v_mov_b32_e32 v99, 0
	v_mov_b32_e32 v100, 0
	v_mov_b32_e32 v101, 0
	s_cmp_lt_u32 s24, 0x4000
	s_cbranch_scc1 .Llg_st1
	s_sub_i32 s75, s24, 0x4000
	s_lshr_b32 s75, s75, 5
	s_mul_i32 s75, s75, 0x3c00
	s_add_u32 s0, s22, s75
	s_addc_u32 s1, s23, 0
	v_add_u32_e32 v104, 0, v1
	v_min_u32_e32 v104, 2, v104
	v_mul_u32_u24_e32 v104, 0x1400, v104
	v_add_u32_e32 v216, v104, v56
	global_load_dwordx4 v[62:65], v216, s[0:1] offset:128
	global_load_dwordx4 v[78:81], v216, s[0:1] offset:144
	v_add_u32_e32 v104, 1, v1
	v_min_u32_e32 v104, 2, v104
	v_mul_u32_u24_e32 v104, 0x1400, v104
	v_add_u32_e32 v217, v104, v56
	global_load_dwordx4 v[82:85], v217, s[0:1] offset:128
	global_load_dwordx4 v[86:89], v217, s[0:1] offset:144
	v_add_u32_e32 v104, 2, v1
	v_min_u32_e32 v104, 2, v104
	v_mul_u32_u24_e32 v104, 0x1400, v104
	v_add_u32_e32 v218, v104, v56
	global_load_dwordx4 v[90:93], v218, s[0:1] offset:128
	global_load_dwordx4 v[98:101], v218, s[0:1] offset:144

; #define LAS __attribute__((address_space(3)))
; DI unsigned cvt_pk_bf16(float lo, float hi) { unsigned r; asm volatile("v_cvt_pk_bf16_f32 %0, %1, %2" : "=v"(r) : "v"(lo), "v"(hi)); return r; }
; template <bool FIRST>
; DI void lru_tile2(const LruP& P, const float* cbuf, int hb, int row, int pos, int fr, int fq, LAS float* xcs) {
;     ...
; #pragma unroll
;     for (int tl = 0; tl < 2; ++tl)
; #pragma unroll
;         for (int ks = 0; ks < 3; ++ks) { const int kc = 32 * ks + 8 * fq; u32x4 w = (u32x4){0u, 0u, 0u, 0u};
;             if (kc < 80) { float x[8];
;                 if (tl == 0) conv_vec<8, FIRST>(x, P.XB, P.cw, P.cb, cbuf, row, pos, 80 * hb + kc); else conv_vec<8, false>(x, P.XB, P.cw, P.cb, nullptr, row + 16, pos + 16, 80 * hb + kc);
;                 w.x = cvt_pk_bf16(x[0], x[1]); w.y = cvt_pk_bf16(x[2], x[3]); w.z = cvt_pk_bf16(x[4], x[5]); w.w = cvt_pk_bf16(x[6], x[7]);
;                 LAS float* xp = xcs + (tl * 16 + fr) * XCP + kc;
;                 *(LAS f32x4*)xp = (f32x4){x[0], x[1], x[2], x[3]}; *(LAS f32x4*)(xp + 4) = (f32x4){x[4], x[5], x[6], x[7]}; }
;             xf[tl][ks] = __builtin_bit_cast(bf16x8, w); }
.Llg_j1:
	v_mov_b32_e32 v50, v212
	v_mov_b32_e32 v51, v213
	v_mov_b32_e32 v52, v214
	v_mov_b32_e32 v53, v215
	v_mov_b32_e32 v58, v238
	v_mov_b32_e32 v59, v239
	v_mov_b32_e32 v60, v240
	v_mov_b32_e32 v61, v241
	v_lshlrev_b32_e32 v102, 16, v156
	v_and_b32_e32 v103, s71, v156
	v_fmac_f32_e32 v50, v180, v102
	v_fmac_f32_e32 v51, v181, v103
	v_lshlrev_b32_e32 v102, 16, v157
	v_and_b32_e32 v103, s71, v157
	v_fmac_f32_e32 v52, v182, v102
	v_fmac_f32_e32 v53, v183, v103
	v_lshlrev_b32_e32 v102, 16, v158
	v_and_b32_e32 v103, s71, v158
	v_fmac_f32_e32 v58, v184, v102
	v_fmac_f32_e32 v59, v185, v103
	v_lshlrev_b32_e32 v102, 16, v159
	v_and_b32_e32 v103, s71, v159
	v_fmac_f32_e32 v60, v186, v102
	v_fmac_f32_e32 v61, v187, v103
	v_lshlrev_b32_e32 v102, 16, v160
	v_and_b32_e32 v103, s71, v160
	v_fmac_f32_e32 v50, v188, v102
	v_fmac_f32_e32 v51, v189, v103
	v_lshlrev_b32_e32 v102, 16, v161
	v_and_b32_e32 v103, s71, v161
	v_fmac_f32_e32 v52, v190, v102
	v_fmac_f32_e32 v53, v191, v103
	v_lshlrev_b32_e32 v102, 16, v162
	v_and_b32_e32 v103, s71, v162
	v_fmac_f32_e32 v58, v192, v102
	v_fmac_f32_e32 v59, v193, v103
	v_lshlrev_b32_e32 v102, 16, v163
	v_and_b32_e32 v103, s71, v163
	v_fmac_f32_e32 v60, v194, v102
	v_fmac_f32_e32 v61, v195, v103
	v_lshlrev_b32_e32 v102, 16, v164
	v_and_b32_e32 v103, s71, v164
	v_fmac_f32_e32 v50, v196, v102
	v_fmac_f32_e32 v51, v197, v103
	v_lshlrev_b32_e32 v102, 16, v165
	v_and_b32_e32 v103, s71, v165
	v_fmac_f32_e32 v52, v198, v102
	v_fmac_f32_e32 v53, v199, v103
	v_lshlrev_b32_e32 v102, 16, v166
	v_and_b32_e32 v103, s71, v166
	v_fmac_f32_e32 v58, v200, v102
	v_fmac_f32_e32 v59, v201, v103
	v_lshlrev_b32_e32 v102, 16, v167
	v_and_b32_e32 v103, s71, v167
	v_fmac_f32_e32 v60, v202, v102
	v_fmac_f32_e32 v61, v203, v103
	v_lshlrev_b32_e32 v102, 16, v168
	v_and_b32_e32 v103, s71, v168
	v_fmac_f32_e32 v50, v204, v102
	v_fmac_f32_e32 v51, v205, v103
	v_lshlrev_b32_e32 v102, 16, v169
	v_and_b32_e32 v103, s71, v169
	v_fmac_f32_e32 v52, v206, v102
	v_fmac_f32_e32 v53, v207, v103
	v_lshlrev_b32_e32 v102, 16, v170
	v_and_b32_e32 v103, s71, v170
	v_fmac_f32_e32 v58, v208, v102
	v_fmac_f32_e32 v59, v209, v103
	v_lshlrev_b32_e32 v102, 16, v171
	v_and_b32_e32 v103, s71, v171
	v_fmac_f32_e32 v60, v210, v102
	v_fmac_f32_e32 v61, v211, v103
	v_cvt_pk_bf16_f32 v6, v42, v43
	v_cvt_pk_bf16_f32 v7, v44, v45
	v_cvt_pk_bf16_f32 v8, v46, v47
	v_cvt_pk_bf16_f32 v9, v48, v49
	ds_write_b128 v131, v[42:45] offset:128
	ds_write_b128 v131, v[46:49] offset:144
	v_cvt_pk_bf16_f32 v34, v50, v51
	v_cvt_pk_bf16_f32 v35, v52, v53
	v_cvt_pk_bf16_f32 v36, v58, v59
	v_cvt_pk_bf16_f32 v37, v60, v61
	ds_write_b128 v131, v[50:53] offset:5504
	ds_write_b128 v131, v[58:61] offset:5520
	s_mov_b32 exec_lo, -1
	s_mov_b32 exec_hi, 0
	global_load_dwordx4 v[180:183], v16, s[84:85] offset:256
	global_load_dwordx4 v[184:187], v16, s[84:85] offset:272
	global_load_dwordx4 v[188:191], v18, s[84:85] offset:256
	global_load_dwordx4 v[192:195], v18, s[84:85] offset:272
	global_load_dwordx4 v[196:199], v54, s[84:85] offset:256
	global_load_dwordx4 v[200:203], v54, s[84:85] offset:272
	global_load_dwordx4 v[204:207], v55, s[84:85] offset:256
	global_load_dwordx4 v[208:211], v55, s[84:85] offset:272
	global_load_dwordx4 v[212:215], v56, s[88:89] offset:256
	global_load_dwordx4 v[238:241], v56, s[88:89] offset:272
	global_load_dwordx4 v[140:143], v11, s[44:45] offset:128
	global_load_dwordx4 v[144:147], v12, s[44:45] offset:128
	global_load_dwordx4 v[148:151], v14, s[44:45] offset:128
	global_load_dwordx4 v[152:155], v15, s[44:45] offset:128
	global_load_dwordx4 v[156:159], v11, s[46:47] offset:128
	global_load_dwordx4 v[160:163], v12, s[46:47] offset:128
	global_load_dwordx4 v[164:167], v14, s[46:47] offset:128
	global_load_dwordx4 v[168:171], v15, s[46:47] offset:128
	s_cmp_eq_u32 s32, 0
	s_cbranch_scc1 .Llg_nf2
	v_mov_b32_e32 v62, 0
	v_mov_b32_e32 v63, 0
	v_mov_b32_e32 v64, 0
	v_mov_b32_e32 v65, 0
	v_mov_b32_e32 v78, 0
	v_mov_b32_e32 v79, 0
	v_mov_b32_e32 v80, 0
	v_mov_b32_e32 v81, 0
	v_mov_b32_e32 v82, 0
	v_mov_b32_e32 v83, 0
	v_mov_b32_e32 v84, 0
	v_mov_b32_e32 v85, 0
	v_mov_b32_e32 v86, 0
	v_mov_b32_e32 v87, 0
	v_mov_b32_e32 v88, 0
	v_mov_b32_e32 v89, 0
	v_mov_b32_e32 v90, 0
	v_mov_b32_e32 v91, 0
	v_mov_b32_e32 v92, 0
	v_mov_b32_e32 v93, 0
	v_mov_b32_e32 v98, 0
	v_mov_b32_e32 v99, 0
	v_mov_b32_e32 v100, 0
	v_mov_b32_e32 v101, 0
	s_cmp_lt_u32 s24, 0x4000
	s_cbranch_scc1 .Llg_st2
	s_sub_i32 s75, s24, 0x4000
	s_lshr_b32 s75, s75, 5
	s_mul_i32 s75, s75, 0x3c00
	s_add_u32 s0, s22, s75
	s_addc_u32 s1, s23, 0
	v_add_u32_e32 v104, 0, v1
	v_min_u32_e32 v104, 2, v104
	v_mul_u32_u24_e32 v104, 0x1400, v104
	v_add_u32_e32 v216, v104, v56
	global_load_dwordx4 v[62:65], v216, s[0:1] offset:256
	global_load_dwordx4 v[78:81], v216, s[0:1] offset:272
	v_add_u32_e32 v104, 1, v1
	v_min_u32_e32 v104, 2, v104
	v_mul_u32_u24_e32 v104, 0x1400, v104
	v_add_u32_e32 v217, v104, v56
	global_load_dwordx4 v[82:85], v217, s[0:1] offset:256
	global_load_dwordx4 v[86:89], v217, s[0:1] offset:272
	v_add_u32_e32 v104, 2, v1
	v_min_u32_e32 v104, 2, v104
	v_mul_u32_u24_e32 v104, 0x1400, v104
	v_add_u32_e32 v218, v104, v56
	global_load_dwordx4 v[90:93], v218, s[0:1] offset:256
	global_load_dwordx4 v[98:101], v218, s[0:1] offset:272

; #define LAS __attribute__((address_space(3)))
; template <bool FIRST>
; DI void lru_tile2(const LruP& P, const float* cbuf, int hb, int row, int pos, int fr, int fq, LAS float* xcs) {
;     ...
;     asm volatile("s_waitcnt lgkmcnt(0)" ::: "memory");
; #pragma unroll
;     for (int nt = 0; nt < 5; ++nt) {
;         const int cur = nt & 1;
;         if (nt < 4) LRU_PRELOAD(cur ^ 1, nt + 1);
;         f32x4 ar[2], ai[2];
;         ar[0] = (f32x4){0.f, 0.f, 0.f, 0.f}; ar[1] = ar[0]; ai[0] = ar[0]; ai[1] = ar[0];
; #pragma unroll
;         for (int ks = 0; ks < 3; ++ks)
; #pragma unroll
;             for (int tl = 0; tl < 2; ++tl) { ar[tl] = __builtin_amdgcn_mfma_f32_16x16x32_bf16(W[cur][ks], xf[tl][ks], ar[tl], 0, 0, 0); ai[tl] = __builtin_amdgcn_mfma_f32_16x16x32_bf16(W[cur][3 + ks], xf[tl][ks], ai[tl], 0, 0, 0); }
;         const int ch = 80 * hb + 16 * nt + 4 * fq; f32x4 av[2], bv[2], xc[2];
; #pragma unroll
;         for (int tl = 0; tl < 2; ++tl) xc[tl] = *(const LAS f32x4*)(xcs + (tl * 16 + fr) * XCP + 16 * nt + 4 * fq);
.Llg_j2:
	v_mov_b32_e32 v50, v212
	v_mov_b32_e32 v51, v213
	v_mov_b32_e32 v52, v214
	v_mov_b32_e32 v53, v215
	v_mov_b32_e32 v58, v238
	v_mov_b32_e32 v59, v239
	v_mov_b32_e32 v60, v240
	v_mov_b32_e32 v61, v241
	v_lshlrev_b32_e32 v102, 16, v156
	v_and_b32_e32 v103, s71, v156
	v_fmac_f32_e32 v50, v180, v102
	v_fmac_f32_e32 v51, v181, v103
	v_lshlrev_b32_e32 v102, 16, v157
	v_and_b32_e32 v103, s71, v157
	v_fmac_f32_e32 v52, v182, v102
	v_fmac_f32_e32 v53, v183, v103
	v_lshlrev_b32_e32 v102, 16, v158
	v_and_b32_e32 v103, s71, v158
	v_fmac_f32_e32 v58, v184, v102
	v_fmac_f32_e32 v59, v185, v103
	v_lshlrev_b32_e32 v102, 16, v159
	v_and_b32_e32 v103, s71, v159
	v_fmac_f32_e32 v60, v186, v102
	v_fmac_f32_e32 v61, v187, v103
	v_lshlrev_b32_e32 v102, 16, v160
	v_and_b32_e32 v103, s71, v160
	v_fmac_f32_e32 v50, v188, v102
	v_fmac_f32_e32 v51, v189, v103
	v_lshlrev_b32_e32 v102, 16, v161
	v_and_b32_e32 v103, s71, v161
	v_fmac_f32_e32 v52, v190, v102
	v_fmac_f32_e32 v53, v191, v103
	v_lshlrev_b32_e32 v102, 16, v162
	v_and_b32_e32 v103, s71, v162
	v_fmac_f32_e32 v58, v192, v102
	v_fmac_f32_e32 v59, v193, v103
	v_lshlrev_b32_e32 v102, 16, v163
	v_and_b32_e32 v103, s71, v163
	v_fmac_f32_e32 v60, v194, v102
	v_fmac_f32_e32 v61, v195, v103
	v_lshlrev_b32_e32 v102, 16, v164
	v_and_b32_e32 v103, s71, v164
	v_fmac_f32_e32 v50, v196, v102
	v_fmac_f32_e32 v51, v197, v103
	v_lshlrev_b32_e32 v102, 16, v165
	v_and_b32_e32 v103, s71, v165
	v_fmac_f32_e32 v52, v198, v102
	v_fmac_f32_e32 v53, v199, v103
	v_lshlrev_b32_e32 v102, 16, v166
	v_and_b32_e32 v103, s71, v166
	v_fmac_f32_e32 v58, v200, v102
	v_fmac_f32_e32 v59, v201, v103
	v_lshlrev_b32_e32 v102, 16, v167
	v_and_b32_e32 v103, s71, v167
	v_fmac_f32_e32 v60, v202, v102
	v_fmac_f32_e32 v61, v203, v103
	v_lshlrev_b32_e32 v102, 16, v168
	v_and_b32_e32 v103, s71, v168
	v_fmac_f32_e32 v50, v204, v102
	v_fmac_f32_e32 v51, v205, v103
	v_lshlrev_b32_e32 v102, 16, v169
	v_and_b32_e32 v103, s71, v169
	v_fmac_f32_e32 v52, v206, v102
	v_fmac_f32_e32 v53, v207, v103
	v_lshlrev_b32_e32 v102, 16, v170
	v_and_b32_e32 v103, s71, v170
	v_fmac_f32_e32 v58, v208, v102
	v_fmac_f32_e32 v59, v209, v103
	v_lshlrev_b32_e32 v102, 16, v171
	v_and_b32_e32 v103, s71, v171
	v_fmac_f32_e32 v60, v210, v102
	v_fmac_f32_e32 v61, v211, v103
	v_cvt_pk_bf16_f32 v22, v42, v43
	v_cvt_pk_bf16_f32 v23, v44, v45
	v_cvt_pk_bf16_f32 v24, v46, v47
	v_cvt_pk_bf16_f32 v25, v48, v49
	ds_write_b128 v131, v[42:45] offset:256
	ds_write_b128 v131, v[46:49] offset:272
	v_cvt_pk_bf16_f32 v38, v50, v51
	v_cvt_pk_bf16_f32 v39, v52, v53
	v_cvt_pk_bf16_f32 v40, v58, v59
	v_cvt_pk_bf16_f32 v41, v60, v61
	ds_write_b128 v131, v[50:53] offset:5632
	ds_write_b128 v131, v[58:61] offset:5648
	s_mov_b64 exec, -1
	v_mov_b32_e32 v252, 0x3e2aaaab
	s_mov_b32 s18, 0xbcf5c28f
	s_mov_b32 s19, 0xbd75c28f
	global_load_dwordx4 v[140:143], v94, s[68:69] offset:0
	global_load_dwordx4 v[152:155], v96, s[68:69] offset:0
	global_load_dwordx4 v[144:147], v94, s[68:69] offset:64
	global_load_dwordx4 v[156:159], v96, s[68:69] offset:64
	global_load_dwordx4 v[148:151], v94, s[68:69] offset:128
	global_load_dwordx4 v[160:163], v96, s[68:69] offset:128
	global_load_dwordx4 v[164:167], v128, s[92:93] offset:0
	global_load_dwordx4 v[168:171], v128, s[96:97] offset:0
	global_load_dwordx4 v[204:207], v128, s[98:99] offset:0
	s_add_u32 s68, s68, 0xc00
	s_addc_u32 s69, s69, 0
	global_load_dwordx4 v[180:183], v94, s[68:69] offset:0
	global_load_dwordx4 v[192:195], v96, s[68:69] offset:0
	global_load_dwordx4 v[184:187], v94, s[68:69] offset:64
	global_load_dwordx4 v[196:199], v96, s[68:69] offset:64
	global_load_dwordx4 v[188:191], v94, s[68:69] offset:128
	global_load_dwordx4 v[200:203], v96, s[68:69] offset:128
	global_load_dwordx4 v[208:211], v128, s[92:93] offset:64
	global_load_dwordx4 v[212:215], v128, s[96:97] offset:64
	global_load_dwordx4 v[238:241], v128, s[98:99] offset:64
	s_add_u32 s68, s68, 0xc00
	s_addc_u32 s69, s69, 0
	ds_read_b128 v[62:65], v237 offset:0
	ds_read_b128 v[78:81], v237 offset:5376
	s_waitcnt vmcnt(9)
	v_mfma_f32_16x16x32_bf16 v[42:45], v[140:143], v[2:5], 0
	v_mfma_f32_16x16x32_bf16 v[46:49], v[152:155], v[2:5], 0
	v_mfma_f32_16x16x32_bf16 v[50:53], v[140:143], v[30:33], 0
	v_mfma_f32_16x16x32_bf16 v[58:61], v[152:155], v[30:33], 0
	v_mfma_f32_16x16x32_bf16 v[42:45], v[144:147], v[6:9], v[42:45]
	v_mfma_f32_16x16x32_bf16 v[46:49], v[156:159], v[6:9], v[46:49]
	v_mfma_f32_16x16x32_bf16 v[50:53], v[144:147], v[34:37], v[50:53]
	v_mfma_f32_16x16x32_bf16 v[58:61], v[156:159], v[34:37], v[58:61]
	v_mfma_f32_16x16x32_bf16 v[42:45], v[148:151], v[22:25], v[42:45]
	v_mfma_f32_16x16x32_bf16 v[46:49], v[160:163], v[22:25], v[46:49]
	v_mfma_f32_16x16x32_bf16 v[50:53], v[148:151], v[38:41], v[50:53]
	v_mfma_f32_16x16x32_bf16 v[58:61], v[160:163], v[38:41], v[58:61]
	s_nop 7
	s_nop 1
	s_waitcnt lgkmcnt(0)
; #define LAS __attribute__((address_space(3)))
; DI unsigned cvt_pk_bf16(float lo, float hi) { unsigned r; asm volatile("v_cvt_pk_bf16_f32 %0, %1, %2" : "=v"(r) : "v"(lo), "v"(hi)); return r; }
; DI float sigmoidf_(float x) { return __builtin_amdgcn_rcpf(1.f + __expf(-x)); }
; template <bool FIRST>
; DI void lru_tile2(const LruP& P, const float* cbuf, int hb, int row, int pos, int fr, int fq, LAS float* xcs) {
;     ...
;         const int ch = 80 * hb + 16 * nt + 4 * fq; f32x4 av[2], bv[2], xc[2];
; #pragma unroll
;         for (int tl = 0; tl < 2; ++tl) xc[tl] = *(const LAS f32x4*)(xcs + (tl * 16 + fr) * XCP + 16 * nt + 4 * fq);
;         const f32x4 ga4 = C[cur][0], gx4 = C[cur][1], sp4 = C[cur][2];
; #pragma unroll
;         for (int tl = 0; tl < 2; ++tl)
; #pragma unroll
;             for (int e = 0; e < 4; ++e) {
;                 const float r = sigmoidf_(ar[tl][e] + ga4[e]), ig = sigmoidf_(ai[tl][e] + gx4[e]);
;                 const float la = -8.f * r * sp4[e]; const float a = __expf(la);
;                 av[tl][e] = (la > -0.03f) ? -la * (1.f + la * (0.5f + la * (0.16666667f + la * 0.041666668f))) : 1.f - a;
;                 const float t = 2.f * la; const float om = (t > -0.06f) ? -t * (1.f + t * (0.5f + t * (0.16666667f + t * 0.041666668f))) : 1.f - a * a;
;                 bv[tl][e] = __builtin_amdgcn_sqrtf(om) * (ig * xc[tl][e]); }
; #pragma unroll
;         for (int tl = 0; tl < 2; ++tl) { u32x4 w;
;             w.x = cvt_pk_bf16(av[tl][0], bv[tl][0]); w.y = cvt_pk_bf16(av[tl][1], bv[tl][1]); w.z = cvt_pk_bf16(av[tl][2], bv[tl][2]); w.w = cvt_pk_bf16(av[tl][3], bv[tl][3]);
;             *(u32x4*)((unsigned*)P.A + (size_t)(row + 16 * tl) * DRNN + ch) = w; } }
	v_add_f32_e32 v42, v42, v164
	v_add_f32_e32 v46, v46, v168
	v_add_f32_e32 v43, v43, v165
	v_add_f32_e32 v47, v47, v169
	v_add_f32_e32 v44, v44, v166
	v_add_f32_e32 v48, v48, v170
	v_add_f32_e32 v45, v45, v167
	v_add_f32_e32 v49, v49, v171
	v_mul_f32_e32 v42, 0xbfb8aa3b, v42
	v_mul_f32_e32 v46, 0xbfb8aa3b, v46
	v_mul_f32_e32 v43, 0xbfb8aa3b, v43
	v_mul_f32_e32 v47, 0xbfb8aa3b, v47
	v_mul_f32_e32 v44, 0xbfb8aa3b, v44
	v_mul_f32_e32 v48, 0xbfb8aa3b, v48
	v_mul_f32_e32 v45, 0xbfb8aa3b, v45
	v_mul_f32_e32 v49, 0xbfb8aa3b, v49
	v_exp_f32_e32 v42, v42
	v_exp_f32_e32 v46, v46
	v_exp_f32_e32 v43, v43
	v_exp_f32_e32 v47, v47
	v_exp_f32_e32 v44, v44
	v_exp_f32_e32 v48, v48
	v_exp_f32_e32 v45, v45
	v_exp_f32_e32 v49, v49
	v_add_f32_e32 v42, 1.0, v42
	v_add_f32_e32 v46, 1.0, v46
	v_add_f32_e32 v43, 1.0, v43
	v_add_f32_e32 v47, 1.0, v47
	v_add_f32_e32 v44, 1.0, v44
	v_add_f32_e32 v48, 1.0, v48
	v_add_f32_e32 v45, 1.0, v45
	v_add_f32_e32 v49, 1.0, v49
	v_rcp_f32_e32 v42, v42
	v_rcp_f32_e32 v46, v46
	v_rcp_f32_e32 v43, v43
	v_rcp_f32_e32 v47, v47
	v_rcp_f32_e32 v44, v44
	v_rcp_f32_e32 v48, v48
	v_rcp_f32_e32 v45, v45
	v_rcp_f32_e32 v49, v49
	v_mul_f32_e32 v82, 0xc1000000, v42
	v_mul_f32_e32 v83, 0xc1000000, v43
	v_mul_f32_e32 v84, 0xc1000000, v44
	v_mul_f32_e32 v85, 0xc1000000, v45
	v_mul_f32_e32 v82, v204, v82
	v_mul_f32_e32 v83, v205, v83
	v_mul_f32_e32 v84, v206, v84
	v_mul_f32_e32 v85, v207, v85
	v_mul_f32_e32 v86, 0x3fb8aa3b, v82
	v_mul_f32_e32 v87, 0x3fb8aa3b, v83
	v_mul_f32_e32 v88, 0x3fb8aa3b, v84
	v_mul_f32_e32 v89, 0x3fb8aa3b, v85
	v_exp_f32_e32 v86, v86
	v_exp_f32_e32 v87, v87
	v_exp_f32_e32 v88, v88
	v_exp_f32_e32 v89, v89
	v_fmamk_f32 v90, v82, 0x3d2aaaab, v252
	v_fmamk_f32 v91, v83, 0x3d2aaaab, v252
	v_fmamk_f32 v92, v84, 0x3d2aaaab, v252
	v_fmamk_f32 v93, v85, 0x3d2aaaab, v252
	v_fma_f32 v90, v82, v90, 0.5
	v_fma_f32 v91, v83, v91, 0.5
	v_fma_f32 v92, v84, v92, 0.5
	v_fma_f32 v93, v85, v93, 0.5
	v_fma_f32 v90, v82, v90, 1.0
	v_fma_f32 v91, v83, v91, 1.0
	v_fma_f32 v92, v84, v92, 1.0
	v_fma_f32 v93, v85, v93, 1.0
	v_mul_f32_e64 v90, v90, -v82
	v_mul_f32_e64 v91, v91, -v83
	v_mul_f32_e64 v92, v92, -v84
	v_mul_f32_e64 v93, v93, -v85
	v_sub_f32_e32 v102, 1.0, v86
	v_sub_f32_e32 v103, 1.0, v87
	v_sub_f32_e32 v104, 1.0, v88
	v_sub_f32_e32 v105, 1.0, v89
	v_cmp_lt_f32_e32 vcc, s18, v82
	s_nop 1
	v_cndmask_b32_e32 v90, v102, v90, vcc
	v_cmp_lt_f32_e32 vcc, s18, v83
	s_nop 1
	v_cndmask_b32_e32 v91, v103, v91, vcc
	v_cmp_lt_f32_e32 vcc, s18, v84
	s_nop 1
	v_cndmask_b32_e32 v92, v104, v92, vcc
	v_cmp_lt_f32_e32 vcc, s18, v85
	s_nop 1
	v_cndmask_b32_e32 v93, v105, v93, vcc
	v_add_f32_e32 v106, v82, v82
	v_add_f32_e32 v107, v83, v83
	v_add_f32_e32 v108, v84, v84
	v_add_f32_e32 v109, v85, v85
	v_fmamk_f32 v98, v106, 0x3d2aaaab, v252
	v_fmamk_f32 v99, v107, 0x3d2aaaab, v252
	v_fmamk_f32 v100, v108, 0x3d2aaaab, v252
	v_fmamk_f32 v101, v109, 0x3d2aaaab, v252
	v_fma_f32 v98, v106, v98, 0.5
	v_fma_f32 v99, v107, v99, 0.5
	v_fma_f32 v100, v108, v100, 0.5
	v_fma_f32 v101, v109, v101, 0.5
	v_fma_f32 v98, v106, v98, 1.0
	v_fma_f32 v99, v107, v99, 1.0
	v_fma_f32 v100, v108, v100, 1.0
	v_fma_f32 v101, v109, v101, 1.0
	v_mul_f32_e64 v98, v98, -v106
	v_mul_f32_e64 v99, v99, -v107
	v_mul_f32_e64 v100, v100, -v108
	v_mul_f32_e64 v101, v101, -v109
	v_fma_f32 v102, -v86, v86, 1.0
	v_fma_f32 v103, -v87, v87, 1.0
	v_fma_f32 v104, -v88, v88, 1.0
	v_fma_f32 v105, -v89, v89, 1.0
	v_cmp_lt_f32_e32 vcc, s19, v106
	s_nop 1
	v_cndmask_b32_e32 v98, v102, v98, vcc
	v_cmp_lt_f32_e32 vcc, s19, v107
	s_nop 1
	v_cndmask_b32_e32 v99, v103, v99, vcc
	v_cmp_lt_f32_e32 vcc, s19, v108
	s_nop 1
	v_cndmask_b32_e32 v100, v104, v100, vcc
	v_cmp_lt_f32_e32 vcc, s19, v109
	s_nop 1
	v_cndmask_b32_e32 v101, v105, v101, vcc
	v_sqrt_f32_e32 v98, v98
	v_sqrt_f32_e32 v99, v99
	v_sqrt_f32_e32 v100, v100
	v_sqrt_f32_e32 v101, v101
	v_mul_f32_e32 v46, v46, v62
	v_mul_f32_e32 v47, v47, v63
	v_mul_f32_e32 v48, v48, v64
	v_mul_f32_e32 v49, v49, v65
	v_mul_f32_e32 v98, v98, v46
	v_mul_f32_e32 v99, v99, v47
	v_mul_f32_e32 v100, v100, v48
	v_mul_f32_e32 v101, v101, v49
	v_cvt_pk_bf16_f32 v242, v90, v98
	v_cvt_pk_bf16_f32 v243, v91, v99
	v_cvt_pk_bf16_f32 v244, v92, v100
	v_cvt_pk_bf16_f32 v245, v93, v101
	global_store_dwordx4 v129, v[242:245], s[78:79]
	v_add_f32_e32 v50, v50, v164
	v_add_f32_e32 v58, v58, v168
	v_add_f32_e32 v51, v51, v165
	v_add_f32_e32 v59, v59, v169
	v_add_f32_e32 v52, v52, v166
	v_add_f32_e32 v60, v60, v170
	v_add_f32_e32 v53, v53, v167
	v_add_f32_e32 v61, v61, v171
	v_mul_f32_e32 v50, 0xbfb8aa3b, v50
	v_mul_f32_e32 v58, 0xbfb8aa3b, v58
	v_mul_f32_e32 v51, 0xbfb8aa3b, v51
	v_mul_f32_e32 v59, 0xbfb8aa3b, v59
	v_mul_f32_e32 v52, 0xbfb8aa3b, v52
	v_mul_f32_e32 v60, 0xbfb8aa3b, v60
	v_mul_f32_e32 v53, 0xbfb8aa3b, v53
	v_mul_f32_e32 v61, 0xbfb8aa3b, v61
	v_exp_f32_e32 v50, v50
	v_exp_f32_e32 v58, v58
	v_exp_f32_e32 v51, v51
	v_exp_f32_e32 v59, v59
	v_exp_f32_e32 v52, v52
	v_exp_f32_e32 v60, v60
	v_exp_f32_e32 v53, v53
	v_exp_f32_e32 v61, v61
	v_add_f32_e32 v50, 1.0, v50
	v_add_f32_e32 v58, 1.0, v58
	v_add_f32_e32 v51, 1.0, v51
	v_add_f32_e32 v59, 1.0, v59
	v_add_f32_e32 v52, 1.0, v52
	v_add_f32_e32 v60, 1.0, v60
	v_add_f32_e32 v53, 1.0, v53
	v_add_f32_e32 v61, 1.0, v61
	v_rcp_f32_e32 v50, v50
	v_rcp_f32_e32 v58, v58
	v_rcp_f32_e32 v51, v51
	v_rcp_f32_e32 v59, v59
	v_rcp_f32_e32 v52, v52
	v_rcp_f32_e32 v60, v60
	v_rcp_f32_e32 v53, v53
	v_rcp_f32_e32 v61, v61
	v_mul_f32_e32 v82, 0xc1000000, v50
	v_mul_f32_e32 v83, 0xc1000000, v51
	v_mul_f32_e32 v84, 0xc1000000, v52
	v_mul_f32_e32 v85, 0xc1000000, v53
	v_mul_f32_e32 v82, v204, v82
	v_mul_f32_e32 v83, v205, v83
	v_mul_f32_e32 v84, v206, v84
; #define LAS __attribute__((address_space(3)))
; DI unsigned cvt_pk_bf16(float lo, float hi) { unsigned r; asm volatile("v_cvt_pk_bf16_f32 %0, %1, %2" : "=v"(r) : "v"(lo), "v"(hi)); return r; }
; DI float sigmoidf_(float x) { return __builtin_amdgcn_rcpf(1.f + __expf(-x)); }
; template <bool FIRST>
; DI void lru_tile2(const LruP& P, const float* cbuf, int hb, int row, int pos, int fr, int fq, LAS float* xcs) {
;     ...
;         const int ch = 80 * hb + 16 * nt + 4 * fq; f32x4 av[2], bv[2], xc[2];
; #pragma unroll
;         for (int tl = 0; tl < 2; ++tl) xc[tl] = *(const LAS f32x4*)(xcs + (tl * 16 + fr) * XCP + 16 * nt + 4 * fq);
;         const f32x4 ga4 = C[cur][0], gx4 = C[cur][1], sp4 = C[cur][2];
; #pragma unroll
;         for (int tl = 0; tl < 2; ++tl)
; #pragma unroll
;             for (int e = 0; e < 4; ++e) {
;                 const float r = sigmoidf_(ar[tl][e] + ga4[e]), ig = sigmoidf_(ai[tl][e] + gx4[e]);
;                 const float la = -8.f * r * sp4[e]; const float a = __expf(la);
;                 av[tl][e] = (la > -0.03f) ? -la * (1.f + la * (0.5f + la * (0.16666667f + la * 0.041666668f))) : 1.f - a;
;                 const float t = 2.f * la; const float om = (t > -0.06f) ? -t * (1.f + t * (0.5f + t * (0.16666667f + t * 0.041666668f))) : 1.f - a * a;
;                 bv[tl][e] = __builtin_amdgcn_sqrtf(om) * (ig * xc[tl][e]); }
; #pragma unroll
;         for (int tl = 0; tl < 2; ++tl) { u32x4 w;
;             w.x = cvt_pk_bf16(av[tl][0], bv[tl][0]); w.y = cvt_pk_bf16(av[tl][1], bv[tl][1]); w.z = cvt_pk_bf16(av[tl][2], bv[tl][2]); w.w = cvt_pk_bf16(av[tl][3], bv[tl][3]);
;             *(u32x4*)((unsigned*)P.A + (size_t)(row + 16 * tl) * DRNN + ch) = w; } }
	v_mul_f32_e32 v85, v207, v85
	v_mul_f32_e32 v86, 0x3fb8aa3b, v82
	v_mul_f32_e32 v87, 0x3fb8aa3b, v83
	v_mul_f32_e32 v88, 0x3fb8aa3b, v84
	v_mul_f32_e32 v89, 0x3fb8aa3b, v85
	v_exp_f32_e32 v86, v86
	v_exp_f32_e32 v87, v87
	v_exp_f32_e32 v88, v88
	v_exp_f32_e32 v89, v89
	v_fmamk_f32 v90, v82, 0x3d2aaaab, v252
	v_fmamk_f32 v91, v83, 0x3d2aaaab, v252
	v_fmamk_f32 v92, v84, 0x3d2aaaab, v252
	v_fmamk_f32 v93, v85, 0x3d2aaaab, v252
	v_fma_f32 v90, v82, v90, 0.5
	v_fma_f32 v91, v83, v91, 0.5
	v_fma_f32 v92, v84, v92, 0.5
	v_fma_f32 v93, v85, v93, 0.5
	v_fma_f32 v90, v82, v90, 1.0
	v_fma_f32 v91, v83, v91, 1.0
	v_fma_f32 v92, v84, v92, 1.0
	v_fma_f32 v93, v85, v93, 1.0
	v_mul_f32_e64 v90, v90, -v82
	v_mul_f32_e64 v91, v91, -v83
	v_mul_f32_e64 v92, v92, -v84
	v_mul_f32_e64 v93, v93, -v85
	v_sub_f32_e32 v102, 1.0, v86
	v_sub_f32_e32 v103, 1.0, v87
	v_sub_f32_e32 v104, 1.0, v88
	v_sub_f32_e32 v105, 1.0, v89
	v_cmp_lt_f32_e32 vcc, s18, v82
	s_nop 1
	v_cndmask_b32_e32 v90, v102, v90, vcc
	v_cmp_lt_f32_e32 vcc, s18, v83
	s_nop 1
	v_cndmask_b32_e32 v91, v103, v91, vcc
	v_cmp_lt_f32_e32 vcc, s18, v84
	s_nop 1
	v_cndmask_b32_e32 v92, v104, v92, vcc
	v_cmp_lt_f32_e32 vcc, s18, v85
	s_nop 1
	v_cndmask_b32_e32 v93, v105, v93, vcc
	v_add_f32_e32 v106, v82, v82
	v_add_f32_e32 v107, v83, v83
	v_add_f32_e32 v108, v84, v84
	v_add_f32_e32 v109, v85, v85
	v_fmamk_f32 v98, v106, 0x3d2aaaab, v252
	v_fmamk_f32 v99, v107, 0x3d2aaaab, v252
	v_fmamk_f32 v100, v108, 0x3d2aaaab, v252
	v_fmamk_f32 v101, v109, 0x3d2aaaab, v252
	v_fma_f32 v98, v106, v98, 0.5
	v_fma_f32 v99, v107, v99, 0.5
	v_fma_f32 v100, v108, v100, 0.5
	v_fma_f32 v101, v109, v101, 0.5
	v_fma_f32 v98, v106, v98, 1.0
	v_fma_f32 v99, v107, v99, 1.0
	v_fma_f32 v100, v108, v100, 1.0
	v_fma_f32 v101, v109, v101, 1.0
	v_mul_f32_e64 v98, v98, -v106
	v_mul_f32_e64 v99, v99, -v107
	v_mul_f32_e64 v100, v100, -v108
	v_mul_f32_e64 v101, v101, -v109
	v_fma_f32 v102, -v86, v86, 1.0
	v_fma_f32 v103, -v87, v87, 1.0
	v_fma_f32 v104, -v88, v88, 1.0
	v_fma_f32 v105, -v89, v89, 1.0
	v_cmp_lt_f32_e32 vcc, s19, v106
	s_nop 1
	v_cndmask_b32_e32 v98, v102, v98, vcc
	v_cmp_lt_f32_e32 vcc, s19, v107
	s_nop 1
	v_cndmask_b32_e32 v99, v103, v99, vcc
	v_cmp_lt_f32_e32 vcc, s19, v108
	s_nop 1
	v_cndmask_b32_e32 v100, v104, v100, vcc
	v_cmp_lt_f32_e32 vcc, s19, v109
	s_nop 1
	v_cndmask_b32_e32 v101, v105, v101, vcc
	v_sqrt_f32_e32 v98, v98
	v_sqrt_f32_e32 v99, v99
	v_sqrt_f32_e32 v100, v100
	v_sqrt_f32_e32 v101, v101
	v_mul_f32_e32 v58, v58, v78
	v_mul_f32_e32 v59, v59, v79
	v_mul_f32_e32 v60, v60, v80
	v_mul_f32_e32 v61, v61, v81
	v_mul_f32_e32 v98, v98, v58
	v_mul_f32_e32 v99, v99, v59
	v_mul_f32_e32 v100, v100, v60
	v_mul_f32_e32 v101, v101, v61
	v_cvt_pk_bf16_f32 v248, v90, v98
	v_cvt_pk_bf16_f32 v249, v91, v99
	v_cvt_pk_bf16_f32 v250, v92, v100
	v_cvt_pk_bf16_f32 v251, v93, v101
	global_store_dwordx4 v130, v[248:251], s[78:79]
	global_load_dwordx4 v[140:143], v94, s[68:69] offset:0
	global_load_dwordx4 v[152:155], v96, s[68:69] offset:0
	global_load_dwordx4 v[144:147], v94, s[68:69] offset:64
	global_load_dwordx4 v[156:159], v96, s[68:69] offset:64
	global_load_dwordx4 v[148:151], v94, s[68:69] offset:128
	global_load_dwordx4 v[160:163], v96, s[68:69] offset:128
	global_load_dwordx4 v[164:167], v128, s[92:93] offset:128
	global_load_dwordx4 v[168:171], v128, s[96:97] offset:128
	global_load_dwordx4 v[204:207], v128, s[98:99] offset:128
	s_add_u32 s68, s68, 0xc00
	s_addc_u32 s69, s69, 0
	ds_read_b128 v[62:65], v237 offset:64
	ds_read_b128 v[78:81], v237 offset:5440
	s_waitcnt vmcnt(11)
	v_mfma_f32_16x16x32_bf16 v[42:45], v[180:183], v[2:5], 0
	v_mfma_f32_16x16x32_bf16 v[46:49], v[192:195], v[2:5], 0
	v_mfma_f32_16x16x32_bf16 v[50:53], v[180:183], v[30:33], 0
	v_mfma_f32_16x16x32_bf16 v[58:61], v[192:195], v[30:33], 0
	v_mfma_f32_16x16x32_bf16 v[42:45], v[184:187], v[6:9], v[42:45]
	v_mfma_f32_16x16x32_bf16 v[46:49], v[196:199], v[6:9], v[46:49]
	v_mfma_f32_16x16x32_bf16 v[50:53], v[184:187], v[34:37], v[50:53]
	v_mfma_f32_16x16x32_bf16 v[58:61], v[196:199], v[34:37], v[58:61]
	v_mfma_f32_16x16x32_bf16 v[42:45], v[188:191], v[22:25], v[42:45]
	v_mfma_f32_16x16x32_bf16 v[46:49], v[200:203], v[22:25], v[46:49]
	v_mfma_f32_16x16x32_bf16 v[50:53], v[188:191], v[38:41], v[50:53]
	v_mfma_f32_16x16x32_bf16 v[58:61], v[200:203], v[38:41], v[58:61]
	s_nop 7
	s_nop 1
	s_waitcnt lgkmcnt(0)
; #define LAS __attribute__((address_space(3)))
; DI unsigned cvt_pk_bf16(float lo, float hi) { unsigned r; asm volatile("v_cvt_pk_bf16_f32 %0, %1, %2" : "=v"(r) : "v"(lo), "v"(hi)); return r; }
; DI float sigmoidf_(float x) { return __builtin_amdgcn_rcpf(1.f + __expf(-x)); }
; template <bool FIRST>
; DI void lru_tile2(const LruP& P, const float* cbuf, int hb, int row, int pos, int fr, int fq, LAS float* xcs) {
;     ...
;         const int ch = 80 * hb + 16 * nt + 4 * fq; f32x4 av[2], bv[2], xc[2];
; #pragma unroll
;         for (int tl = 0; tl < 2; ++tl) xc[tl] = *(const LAS f32x4*)(xcs + (tl * 16 + fr) * XCP + 16 * nt + 4 * fq);
;         const f32x4 ga4 = C[cur][0], gx4 = C[cur][1], sp4 = C[cur][2];
; #pragma unroll
;         for (int tl = 0; tl < 2; ++tl)
; #pragma unroll
;             for (int e = 0; e < 4; ++e) {
;                 const float r = sigmoidf_(ar[tl][e] + ga4[e]), ig = sigmoidf_(ai[tl][e] + gx4[e]);
;                 const float la = -8.f * r * sp4[e]; const float a = __expf(la);
;                 av[tl][e] = (la > -0.03f) ? -la * (1.f + la * (0.5f + la * (0.16666667f + la * 0.041666668f))) : 1.f - a;
;                 const float t = 2.f * la; const float om = (t > -0.06f) ? -t * (1.f + t * (0.5f + t * (0.16666667f + t * 0.041666668f))) : 1.f - a * a;
;                 bv[tl][e] = __builtin_amdgcn_sqrtf(om) * (ig * xc[tl][e]); }
; #pragma unroll
;         for (int tl = 0; tl < 2; ++tl) { u32x4 w;
;             w.x = cvt_pk_bf16(av[tl][0], bv[tl][0]); w.y = cvt_pk_bf16(av[tl][1], bv[tl][1]); w.z = cvt_pk_bf16(av[tl][2], bv[tl][2]); w.w = cvt_pk_bf16(av[tl][3], bv[tl][3]);
;             *(u32x4*)((unsigned*)P.A + (size_t)(row + 16 * tl) * DRNN + ch) = w; } }
	v_add_f32_e32 v42, v42, v208
	v_add_f32_e32 v46, v46, v212
	v_add_f32_e32 v43, v43, v209
	v_add_f32_e32 v47, v47, v213
	v_add_f32_e32 v44, v44, v210
	v_add_f32_e32 v48, v48, v214
	v_add_f32_e32 v45, v45, v211
	v_add_f32_e32 v49, v49, v215
	v_mul_f32_e32 v42, 0xbfb8aa3b, v42
	v_mul_f32_e32 v46, 0xbfb8aa3b, v46
	v_mul_f32_e32 v43, 0xbfb8aa3b, v43
	v_mul_f32_e32 v47, 0xbfb8aa3b, v47
	v_mul_f32_e32 v44, 0xbfb8aa3b, v44
	v_mul_f32_e32 v48, 0xbfb8aa3b, v48
	v_mul_f32_e32 v45, 0xbfb8aa3b, v45
	v_mul_f32_e32 v49, 0xbfb8aa3b, v49
	v_exp_f32_e32 v42, v42
	v_exp_f32_e32 v46, v46
	v_exp_f32_e32 v43, v43
	v_exp_f32_e32 v47, v47
	v_exp_f32_e32 v44, v44
	v_exp_f32_e32 v48, v48
	v_exp_f32_e32 v45, v45
	v_exp_f32_e32 v49, v49
	v_add_f32_e32 v42, 1.0, v42
	v_add_f32_e32 v46, 1.0, v46
	v_add_f32_e32 v43, 1.0, v43
	v_add_f32_e32 v47, 1.0, v47
	v_add_f32_e32 v44, 1.0, v44
	v_add_f32_e32 v48, 1.0, v48
	v_add_f32_e32 v45, 1.0, v45
	v_add_f32_e32 v49, 1.0, v49
	v_rcp_f32_e32 v42, v42
	v_rcp_f32_e32 v46, v46
	v_rcp_f32_e32 v43, v43
	v_rcp_f32_e32 v47, v47
	v_rcp_f32_e32 v44, v44
	v_rcp_f32_e32 v48, v48
	v_rcp_f32_e32 v45, v45
	v_rcp_f32_e32 v49, v49
	v_mul_f32_e32 v82, 0xc1000000, v42
	v_mul_f32_e32 v83, 0xc1000000, v43
	v_mul_f32_e32 v84, 0xc1000000, v44
	v_mul_f32_e32 v85, 0xc1000000, v45
	v_mul_f32_e32 v82, v238, v82
	v_mul_f32_e32 v83, v239, v83
	v_mul_f32_e32 v84, v240, v84
	v_mul_f32_e32 v85, v241, v85
	v_mul_f32_e32 v86, 0x3fb8aa3b, v82
	v_mul_f32_e32 v87, 0x3fb8aa3b, v83
	v_mul_f32_e32 v88, 0x3fb8aa3b, v84
	v_mul_f32_e32 v89, 0x3fb8aa3b, v85
	v_exp_f32_e32 v86, v86
	v_exp_f32_e32 v87, v87
	v_exp_f32_e32 v88, v88
	v_exp_f32_e32 v89, v89
	v_fmamk_f32 v90, v82, 0x3d2aaaab, v252
	v_fmamk_f32 v91, v83, 0x3d2aaaab, v252
	v_fmamk_f32 v92, v84, 0x3d2aaaab, v252
	v_fmamk_f32 v93, v85, 0x3d2aaaab, v252
	v_fma_f32 v90, v82, v90, 0.5
	v_fma_f32 v91, v83, v91, 0.5
	v_fma_f32 v92, v84, v92, 0.5
	v_fma_f32 v93, v85, v93, 0.5
	v_fma_f32 v90, v82, v90, 1.0
	v_fma_f32 v91, v83, v91, 1.0
	v_fma_f32 v92, v84, v92, 1.0
	v_fma_f32 v93, v85, v93, 1.0
	v_mul_f32_e64 v90, v90, -v82
	v_mul_f32_e64 v91, v91, -v83
	v_mul_f32_e64 v92, v92, -v84
	v_mul_f32_e64 v93, v93, -v85
	v_sub_f32_e32 v102, 1.0, v86
	v_sub_f32_e32 v103, 1.0, v87
	v_sub_f32_e32 v104, 1.0, v88
	v_sub_f32_e32 v105, 1.0, v89
	v_cmp_lt_f32_e32 vcc, s18, v82
	s_nop 1
	v_cndmask_b32_e32 v90, v102, v90, vcc
	v_cmp_lt_f32_e32 vcc, s18, v83
	s_nop 1
	v_cndmask_b32_e32 v91, v103, v91, vcc
	v_cmp_lt_f32_e32 vcc, s18, v84
	s_nop 1
	v_cndmask_b32_e32 v92, v104, v92, vcc
	v_cmp_lt_f32_e32 vcc, s18, v85
	s_nop 1
	v_cndmask_b32_e32 v93, v105, v93, vcc
	v_add_f32_e32 v106, v82, v82
	v_add_f32_e32 v107, v83, v83
	v_add_f32_e32 v108, v84, v84
	v_add_f32_e32 v109, v85, v85
	v_fmamk_f32 v98, v106, 0x3d2aaaab, v252
	v_fmamk_f32 v99, v107, 0x3d2aaaab, v252
	v_fmamk_f32 v100, v108, 0x3d2aaaab, v252
	v_fmamk_f32 v101, v109, 0x3d2aaaab, v252
	v_fma_f32 v98, v106, v98, 0.5
	v_fma_f32 v99, v107, v99, 0.5
	v_fma_f32 v100, v108, v100, 0.5
	v_fma_f32 v101, v109, v101, 0.5
	v_fma_f32 v98, v106, v98, 1.0
	v_fma_f32 v99, v107, v99, 1.0
	v_fma_f32 v100, v108, v100, 1.0
	v_fma_f32 v101, v109, v101, 1.0
	v_mul_f32_e64 v98, v98, -v106
	v_mul_f32_e64 v99, v99, -v107
	v_mul_f32_e64 v100, v100, -v108
	v_mul_f32_e64 v101, v101, -v109
	v_fma_f32 v102, -v86, v86, 1.0
	v_fma_f32 v103, -v87, v87, 1.0
	v_fma_f32 v104, -v88, v88, 1.0
	v_fma_f32 v105, -v89, v89, 1.0
	v_cmp_lt_f32_e32 vcc, s19, v106
	s_nop 1
	v_cndmask_b32_e32 v98, v102, v98, vcc
	v_cmp_lt_f32_e32 vcc, s19, v107
	s_nop 1
	v_cndmask_b32_e32 v99, v103, v99, vcc
	v_cmp_lt_f32_e32 vcc, s19, v108
	s_nop 1
	v_cndmask_b32_e32 v100, v104, v100, vcc
	v_cmp_lt_f32_e32 vcc, s19, v109
	s_nop 1
	v_cndmask_b32_e32 v101, v105, v101, vcc
	v_sqrt_f32_e32 v98, v98
	v_sqrt_f32_e32 v99, v99
	v_sqrt_f32_e32 v100, v100
	v_sqrt_f32_e32 v101, v101
	v_mul_f32_e32 v46, v46, v62
	v_mul_f32_e32 v47, v47, v63
	v_mul_f32_e32 v48, v48, v64
	v_mul_f32_e32 v49, v49, v65
	v_mul_f32_e32 v98, v98, v46
	v_mul_f32_e32 v99, v99, v47
	v_mul_f32_e32 v100, v100, v48
	v_mul_f32_e32 v101, v101, v49
	v_cvt_pk_bf16_f32 v242, v90, v98
	v_cvt_pk_bf16_f32 v243, v91, v99
	v_cvt_pk_bf16_f32 v244, v92, v100
	v_cvt_pk_bf16_f32 v245, v93, v101
	global_store_dwordx4 v129, v[242:245], s[78:79] offset:64
	v_add_f32_e32 v50, v50, v208
	v_add_f32_e32 v58, v58, v212
	v_add_f32_e32 v51, v51, v209
	v_add_f32_e32 v59, v59, v213
	v_add_f32_e32 v52, v52, v210
	v_add_f32_e32 v60, v60, v214
	v_add_f32_e32 v53, v53, v211
	v_add_f32_e32 v61, v61, v215
	v_mul_f32_e32 v50, 0xbfb8aa3b, v50
	v_mul_f32_e32 v58, 0xbfb8aa3b, v58
	v_mul_f32_e32 v51, 0xbfb8aa3b, v51
	v_mul_f32_e32 v59, 0xbfb8aa3b, v59
	v_mul_f32_e32 v52, 0xbfb8aa3b, v52
	v_mul_f32_e32 v60, 0xbfb8aa3b, v60
	v_mul_f32_e32 v53, 0xbfb8aa3b, v53
	v_mul_f32_e32 v61, 0xbfb8aa3b, v61
	v_exp_f32_e32 v50, v50
	v_exp_f32_e32 v58, v58
	v_exp_f32_e32 v51, v51
	v_exp_f32_e32 v59, v59
	v_exp_f32_e32 v52, v52
	v_exp_f32_e32 v60, v60
	v_exp_f32_e32 v53, v53
	v_exp_f32_e32 v61, v61
	v_add_f32_e32 v50, 1.0, v50
	v_add_f32_e32 v58, 1.0, v58
	v_add_f32_e32 v51, 1.0, v51
	v_add_f32_e32 v59, 1.0, v59
	v_add_f32_e32 v52, 1.0, v52
	v_add_f32_e32 v60, 1.0, v60
	v_add_f32_e32 v53, 1.0, v53
	v_add_f32_e32 v61, 1.0, v61
	v_rcp_f32_e32 v50, v50
	v_rcp_f32_e32 v58, v58
	v_rcp_f32_e32 v51, v51
	v_rcp_f32_e32 v59, v59
	v_rcp_f32_e32 v52, v52
	v_rcp_f32_e32 v60, v60
	v_rcp_f32_e32 v53, v53
	v_rcp_f32_e32 v61, v61
	v_mul_f32_e32 v82, 0xc1000000, v50
	v_mul_f32_e32 v83, 0xc1000000, v51
	v_mul_f32_e32 v84, 0xc1000000, v52
	v_mul_f32_e32 v85, 0xc1000000, v53
	v_mul_f32_e32 v82, v238, v82
	v_mul_f32_e32 v83, v239, v83
	v_mul_f32_e32 v84, v240, v84
; #define LAS __attribute__((address_space(3)))
; DI unsigned cvt_pk_bf16(float lo, float hi) { unsigned r; asm volatile("v_cvt_pk_bf16_f32 %0, %1, %2" : "=v"(r) : "v"(lo), "v"(hi)); return r; }
; DI float sigmoidf_(float x) { return __builtin_amdgcn_rcpf(1.f + __expf(-x)); }
; template <bool FIRST>
; DI void lru_tile2(const LruP& P, const float* cbuf, int hb, int row, int pos, int fr, int fq, LAS float* xcs) {
;     ...
;     for (int nt = 0; nt < 5; ++nt) {
;         const int cur = nt & 1;
;         if (nt < 4) LRU_PRELOAD(cur ^ 1, nt + 1);
;         f32x4 ar[2], ai[2];
;         ar[0] = (f32x4){0.f, 0.f, 0.f, 0.f}; ar[1] = ar[0]; ai[0] = ar[0]; ai[1] = ar[0];
; #pragma unroll
;         for (int ks = 0; ks < 3; ++ks)
; #pragma unroll
;             for (int tl = 0; tl < 2; ++tl) { ar[tl] = __builtin_amdgcn_mfma_f32_16x16x32_bf16(W[cur][ks], xf[tl][ks], ar[tl], 0, 0, 0); ai[tl] = __builtin_amdgcn_mfma_f32_16x16x32_bf16(W[cur][3 + ks], xf[tl][ks], ai[tl], 0, 0, 0); }
;         const int ch = 80 * hb + 16 * nt + 4 * fq; f32x4 av[2], bv[2], xc[2];
; #pragma unroll
;         for (int tl = 0; tl < 2; ++tl) xc[tl] = *(const LAS f32x4*)(xcs + (tl * 16 + fr) * XCP + 16 * nt + 4 * fq);
;         const f32x4 ga4 = C[cur][0], gx4 = C[cur][1], sp4 = C[cur][2];
; #pragma unroll
;         for (int tl = 0; tl < 2; ++tl)
; #pragma unroll
;             for (int e = 0; e < 4; ++e) {
;                 const float r = sigmoidf_(ar[tl][e] + ga4[e]), ig = sigmoidf_(ai[tl][e] + gx4[e]);
;                 const float la = -8.f * r * sp4[e]; const float a = __expf(la);
;                 av[tl][e] = (la > -0.03f) ? -la * (1.f + la * (0.5f + la * (0.16666667f + la * 0.041666668f))) : 1.f - a;
;                 const float t = 2.f * la; const float om = (t > -0.06f) ? -t * (1.f + t * (0.5f + t * (0.16666667f + t * 0.041666668f))) : 1.f - a * a;
;                 bv[tl][e] = __builtin_amdgcn_sqrtf(om) * (ig * xc[tl][e]); }
; #pragma unroll
;         for (int tl = 0; tl < 2; ++tl) { u32x4 w;
;             w.x = cvt_pk_bf16(av[tl][0], bv[tl][0]); w.y = cvt_pk_bf16(av[tl][1], bv[tl][1]); w.z = cvt_pk_bf16(av[tl][2], bv[tl][2]); w.w = cvt_pk_bf16(av[tl][3], bv[tl][3]);
;             *(u32x4*)((unsigned*)P.A + (size_t)(row + 16 * tl) * DRNN + ch) = w; } }
	v_mul_f32_e32 v85, v241, v85
	v_mul_f32_e32 v86, 0x3fb8aa3b, v82
	v_mul_f32_e32 v87, 0x3fb8aa3b, v83
	v_mul_f32_e32 v88, 0x3fb8aa3b, v84
	v_mul_f32_e32 v89, 0x3fb8aa3b, v85
	v_exp_f32_e32 v86, v86
	v_exp_f32_e32 v87, v87
	v_exp_f32_e32 v88, v88
	v_exp_f32_e32 v89, v89
	v_fmamk_f32 v90, v82, 0x3d2aaaab, v252
	v_fmamk_f32 v91, v83, 0x3d2aaaab, v252
	v_fmamk_f32 v92, v84, 0x3d2aaaab, v252
	v_fmamk_f32 v93, v85, 0x3d2aaaab, v252
	v_fma_f32 v90, v82, v90, 0.5
	v_fma_f32 v91, v83, v91, 0.5
	v_fma_f32 v92, v84, v92, 0.5
	v_fma_f32 v93, v85, v93, 0.5
	v_fma_f32 v90, v82, v90, 1.0
	v_fma_f32 v91, v83, v91, 1.0
	v_fma_f32 v92, v84, v92, 1.0
	v_fma_f32 v93, v85, v93, 1.0
	v_mul_f32_e64 v90, v90, -v82
	v_mul_f32_e64 v91, v91, -v83
	v_mul_f32_e64 v92, v92, -v84
	v_mul_f32_e64 v93, v93, -v85
	v_sub_f32_e32 v102, 1.0, v86
	v_sub_f32_e32 v103, 1.0, v87
	v_sub_f32_e32 v104, 1.0, v88
	v_sub_f32_e32 v105, 1.0, v89
	v_cmp_lt_f32_e32 vcc, s18, v82
	s_nop 1
	v_cndmask_b32_e32 v90, v102, v90, vcc
	v_cmp_lt_f32_e32 vcc, s18, v83
	s_nop 1
	v_cndmask_b32_e32 v91, v103, v91, vcc
	v_cmp_lt_f32_e32 vcc, s18, v84
	s_nop 1
	v_cndmask_b32_e32 v92, v104, v92, vcc
	v_cmp_lt_f32_e32 vcc, s18, v85
	s_nop 1
	v_cndmask_b32_e32 v93, v105, v93, vcc
	v_add_f32_e32 v106, v82, v82
	v_add_f32_e32 v107, v83, v83
	v_add_f32_e32 v108, v84, v84
	v_add_f32_e32 v109, v85, v85
	v_fmamk_f32 v98, v106, 0x3d2aaaab, v252
	v_fmamk_f32 v99, v107, 0x3d2aaaab, v252
	v_fmamk_f32 v100, v108, 0x3d2aaaab, v252
	v_fmamk_f32 v101, v109, 0x3d2aaaab, v252
	v_fma_f32 v98, v106, v98, 0.5
	v_fma_f32 v99, v107, v99, 0.5
	v_fma_f32 v100, v108, v100, 0.5
	v_fma_f32 v101, v109, v101, 0.5
	v_fma_f32 v98, v106, v98, 1.0
	v_fma_f32 v99, v107, v99, 1.0
	v_fma_f32 v100, v108, v100, 1.0
	v_fma_f32 v101, v109, v101, 1.0
	v_mul_f32_e64 v98, v98, -v106
	v_mul_f32_e64 v99, v99, -v107
	v_mul_f32_e64 v100, v100, -v108
	v_mul_f32_e64 v101, v101, -v109
	v_fma_f32 v102, -v86, v86, 1.0
	v_fma_f32 v103, -v87, v87, 1.0
	v_fma_f32 v104, -v88, v88, 1.0
	v_fma_f32 v105, -v89, v89, 1.0
	v_cmp_lt_f32_e32 vcc, s19, v106
	s_nop 1
	v_cndmask_b32_e32 v98, v102, v98, vcc
	v_cmp_lt_f32_e32 vcc, s19, v107
	s_nop 1
	v_cndmask_b32_e32 v99, v103, v99, vcc
	v_cmp_lt_f32_e32 vcc, s19, v108
	s_nop 1
	v_cndmask_b32_e32 v100, v104, v100, vcc
	v_cmp_lt_f32_e32 vcc, s19, v109
	s_nop 1
	v_cndmask_b32_e32 v101, v105, v101, vcc
	v_sqrt_f32_e32 v98, v98
	v_sqrt_f32_e32 v99, v99
	v_sqrt_f32_e32 v100, v100
	v_sqrt_f32_e32 v101, v101
	v_mul_f32_e32 v58, v58, v78
	v_mul_f32_e32 v59, v59, v79
	v_mul_f32_e32 v60, v60, v80
	v_mul_f32_e32 v61, v61, v81
	v_mul_f32_e32 v98, v98, v58
	v_mul_f32_e32 v99, v99, v59
	v_mul_f32_e32 v100, v100, v60
	v_mul_f32_e32 v101, v101, v61
	v_cvt_pk_bf16_f32 v248, v90, v98
	v_cvt_pk_bf16_f32 v249, v91, v99
	v_cvt_pk_bf16_f32 v250, v92, v100
	v_cvt_pk_bf16_f32 v251, v93, v101
	global_store_dwordx4 v130, v[248:251], s[78:79] offset:64
	global_load_dwordx4 v[180:183], v94, s[68:69] offset:0
	global_load_dwordx4 v[192:195], v96, s[68:69] offset:0
	global_load_dwordx4 v[184:187], v94, s[68:69] offset:64
	global_load_dwordx4 v[196:199], v96, s[68:69] offset:64
	global_load_dwordx4 v[188:191], v94, s[68:69] offset:128
	global_load_dwordx4 v[200:203], v96, s[68:69] offset:128
	global_load_dwordx4 v[208:211], v128, s[92:93] offset:192
	global_load_dwordx4 v[212:215], v128, s[96:97] offset:192
	global_load_dwordx4 v[238:241], v128, s[98:99] offset:192
	s_add_u32 s68, s68, 0xc00
	s_addc_u32 s69, s69, 0
	ds_read_b128 v[62:65], v237 offset:128
	ds_read_b128 v[78:81], v237 offset:5504
	s_waitcnt vmcnt(11)
	v_mfma_f32_16x16x32_bf16 v[42:45], v[140:143], v[2:5], 0
	v_mfma_f32_16x16x32_bf16 v[46:49], v[152:155], v[2:5], 0
	v_mfma_f32_16x16x32_bf16 v[50:53], v[140:143], v[30:33], 0
	v_mfma_f32_16x16x32_bf16 v[58:61], v[152:155], v[30:33], 0
	v_mfma_f32_16x16x32_bf16 v[42:45], v[144:147], v[6:9], v[42:45]
	v_mfma_f32_16x16x32_bf16 v[46:49], v[156:159], v[6:9], v[46:49]
	v_mfma_f32_16x16x32_bf16 v[50:53], v[144:147], v[34:37], v[50:53]
	v_mfma_f32_16x16x32_bf16 v[58:61], v[156:159], v[34:37], v[58:61]
	v_mfma_f32_16x16x32_bf16 v[42:45], v[148:151], v[22:25], v[42:45]
	v_mfma_f32_16x16x32_bf16 v[46:49], v[160:163], v[22:25], v[46:49]
	v_mfma_f32_16x16x32_bf16 v[50:53], v[148:151], v[38:41], v[50:53]
	v_mfma_f32_16x16x32_bf16 v[58:61], v[160:163], v[38:41], v[58:61]
	s_nop 7
	s_nop 1
	s_waitcnt lgkmcnt(0)
; #define LAS __attribute__((address_space(3)))
; DI unsigned cvt_pk_bf16(float lo, float hi) { unsigned r; asm volatile("v_cvt_pk_bf16_f32 %0, %1, %2" : "=v"(r) : "v"(lo), "v"(hi)); return r; }
; DI float sigmoidf_(float x) { return __builtin_amdgcn_rcpf(1.f + __expf(-x)); }
; template <bool FIRST>
; DI void lru_tile2(const LruP& P, const float* cbuf, int hb, int row, int pos, int fr, int fq, LAS float* xcs) {
;     ...
;         const int ch = 80 * hb + 16 * nt + 4 * fq; f32x4 av[2], bv[2], xc[2];
; #pragma unroll
;         for (int tl = 0; tl < 2; ++tl) xc[tl] = *(const LAS f32x4*)(xcs + (tl * 16 + fr) * XCP + 16 * nt + 4 * fq);
;         const f32x4 ga4 = C[cur][0], gx4 = C[cur][1], sp4 = C[cur][2];
; #pragma unroll
;         for (int tl = 0; tl < 2; ++tl)
; #pragma unroll
;             for (int e = 0; e < 4; ++e) {
;                 const float r = sigmoidf_(ar[tl][e] + ga4[e]), ig = sigmoidf_(ai[tl][e] + gx4[e]);
;                 const float la = -8.f * r * sp4[e]; const float a = __expf(la);
;                 av[tl][e] = (la > -0.03f) ? -la * (1.f + la * (0.5f + la * (0.16666667f + la * 0.041666668f))) : 1.f - a;
;                 const float t = 2.f * la; const float om = (t > -0.06f) ? -t * (1.f + t * (0.5f + t * (0.16666667f + t * 0.041666668f))) : 1.f - a * a;
;                 bv[tl][e] = __builtin_amdgcn_sqrtf(om) * (ig * xc[tl][e]); }
; #pragma unroll
;         for (int tl = 0; tl < 2; ++tl) { u32x4 w;
;             w.x = cvt_pk_bf16(av[tl][0], bv[tl][0]); w.y = cvt_pk_bf16(av[tl][1], bv[tl][1]); w.z = cvt_pk_bf16(av[tl][2], bv[tl][2]); w.w = cvt_pk_bf16(av[tl][3], bv[tl][3]);
;             *(u32x4*)((unsigned*)P.A + (size_t)(row + 16 * tl) * DRNN + ch) = w; } }
	v_add_f32_e32 v42, v42, v164
	v_add_f32_e32 v46, v46, v168
	v_add_f32_e32 v43, v43, v165
	v_add_f32_e32 v47, v47, v169
	v_add_f32_e32 v44, v44, v166
	v_add_f32_e32 v48, v48, v170
	v_add_f32_e32 v45, v45, v167
	v_add_f32_e32 v49, v49, v171
	v_mul_f32_e32 v42, 0xbfb8aa3b, v42
	v_mul_f32_e32 v46, 0xbfb8aa3b, v46
	v_mul_f32_e32 v43, 0xbfb8aa3b, v43
	v_mul_f32_e32 v47, 0xbfb8aa3b, v47
	v_mul_f32_e32 v44, 0xbfb8aa3b, v44
	v_mul_f32_e32 v48, 0xbfb8aa3b, v48
	v_mul_f32_e32 v45, 0xbfb8aa3b, v45
	v_mul_f32_e32 v49, 0xbfb8aa3b, v49
	v_exp_f32_e32 v42, v42
	v_exp_f32_e32 v46, v46
	v_exp_f32_e32 v43, v43
	v_exp_f32_e32 v47, v47
	v_exp_f32_e32 v44, v44
	v_exp_f32_e32 v48, v48
	v_exp_f32_e32 v45, v45
	v_exp_f32_e32 v49, v49
	v_add_f32_e32 v42, 1.0, v42
	v_add_f32_e32 v46, 1.0, v46
	v_add_f32_e32 v43, 1.0, v43
	v_add_f32_e32 v47, 1.0, v47
	v_add_f32_e32 v44, 1.0, v44
	v_add_f32_e32 v48, 1.0, v48
	v_add_f32_e32 v45, 1.0, v45
	v_add_f32_e32 v49, 1.0, v49
	v_rcp_f32_e32 v42, v42
	v_rcp_f32_e32 v46, v46
	v_rcp_f32_e32 v43, v43
	v_rcp_f32_e32 v47, v47
	v_rcp_f32_e32 v44, v44
	v_rcp_f32_e32 v48, v48
	v_rcp_f32_e32 v45, v45
	v_rcp_f32_e32 v49, v49
	v_mul_f32_e32 v82, 0xc1000000, v42
	v_mul_f32_e32 v83, 0xc1000000, v43
	v_mul_f32_e32 v84, 0xc1000000, v44
	v_mul_f32_e32 v85, 0xc1000000, v45
	v_mul_f32_e32 v82, v204, v82
	v_mul_f32_e32 v83, v205, v83
	v_mul_f32_e32 v84, v206, v84
	v_mul_f32_e32 v85, v207, v85
	v_mul_f32_e32 v86, 0x3fb8aa3b, v82
	v_mul_f32_e32 v87, 0x3fb8aa3b, v83
	v_mul_f32_e32 v88, 0x3fb8aa3b, v84
	v_mul_f32_e32 v89, 0x3fb8aa3b, v85
	v_exp_f32_e32 v86, v86
	v_exp_f32_e32 v87, v87
	v_exp_f32_e32 v88, v88
	v_exp_f32_e32 v89, v89
	v_fmamk_f32 v90, v82, 0x3d2aaaab, v252
	v_fmamk_f32 v91, v83, 0x3d2aaaab, v252
	v_fmamk_f32 v92, v84, 0x3d2aaaab, v252
	v_fmamk_f32 v93, v85, 0x3d2aaaab, v252
	v_fma_f32 v90, v82, v90, 0.5
	v_fma_f32 v91, v83, v91, 0.5
	v_fma_f32 v92, v84, v92, 0.5
	v_fma_f32 v93, v85, v93, 0.5
	v_fma_f32 v90, v82, v90, 1.0
	v_fma_f32 v91, v83, v91, 1.0
	v_fma_f32 v92, v84, v92, 1.0
	v_fma_f32 v93, v85, v93, 1.0
	v_mul_f32_e64 v90, v90, -v82
	v_mul_f32_e64 v91, v91, -v83
	v_mul_f32_e64 v92, v92, -v84
	v_mul_f32_e64 v93, v93, -v85
	v_sub_f32_e32 v102, 1.0, v86
	v_sub_f32_e32 v103, 1.0, v87
	v_sub_f32_e32 v104, 1.0, v88
	v_sub_f32_e32 v105, 1.0, v89
	v_cmp_lt_f32_e32 vcc, s18, v82
	s_nop 1
	v_cndmask_b32_e32 v90, v102, v90, vcc
	v_cmp_lt_f32_e32 vcc, s18, v83
	s_nop 1
	v_cndmask_b32_e32 v91, v103, v91, vcc
	v_cmp_lt_f32_e32 vcc, s18, v84
	s_nop 1
	v_cndmask_b32_e32 v92, v104, v92, vcc
	v_cmp_lt_f32_e32 vcc, s18, v85
	s_nop 1
	v_cndmask_b32_e32 v93, v105, v93, vcc
	v_add_f32_e32 v106, v82, v82
	v_add_f32_e32 v107, v83, v83
	v_add_f32_e32 v108, v84, v84
	v_add_f32_e32 v109, v85, v85
	v_fmamk_f32 v98, v106, 0x3d2aaaab, v252
	v_fmamk_f32 v99, v107, 0x3d2aaaab, v252
	v_fmamk_f32 v100, v108, 0x3d2aaaab, v252
	v_fmamk_f32 v101, v109, 0x3d2aaaab, v252
	v_fma_f32 v98, v106, v98, 0.5
	v_fma_f32 v99, v107, v99, 0.5
	v_fma_f32 v100, v108, v100, 0.5
	v_fma_f32 v101, v109, v101, 0.5
	v_fma_f32 v98, v106, v98, 1.0
	v_fma_f32 v99, v107, v99, 1.0
	v_fma_f32 v100, v108, v100, 1.0
	v_fma_f32 v101, v109, v101, 1.0
	v_mul_f32_e64 v98, v98, -v106
	v_mul_f32_e64 v99, v99, -v107
	v_mul_f32_e64 v100, v100, -v108
	v_mul_f32_e64 v101, v101, -v109
	v_fma_f32 v102, -v86, v86, 1.0
	v_fma_f32 v103, -v87, v87, 1.0
	v_fma_f32 v104, -v88, v88, 1.0
	v_fma_f32 v105, -v89, v89, 1.0
	v_cmp_lt_f32_e32 vcc, s19, v106
	s_nop 1
	v_cndmask_b32_e32 v98, v102, v98, vcc
	v_cmp_lt_f32_e32 vcc, s19, v107
	s_nop 1
	v_cndmask_b32_e32 v99, v103, v99, vcc
	v_cmp_lt_f32_e32 vcc, s19, v108
	s_nop 1
	v_cndmask_b32_e32 v100, v104, v100, vcc
	v_cmp_lt_f32_e32 vcc, s19, v109
	s_nop 1
	v_cndmask_b32_e32 v101, v105, v101, vcc
	v_sqrt_f32_e32 v98, v98
	v_sqrt_f32_e32 v99, v99
	v_sqrt_f32_e32 v100, v100
	v_sqrt_f32_e32 v101, v101
	v_mul_f32_e32 v46, v46, v62
	v_mul_f32_e32 v47, v47, v63
	v_mul_f32_e32 v48, v48, v64
	v_mul_f32_e32 v49, v49, v65
	v_mul_f32_e32 v98, v98, v46
	v_mul_f32_e32 v99, v99, v47
	v_mul_f32_e32 v100, v100, v48
	v_mul_f32_e32 v101, v101, v49
	v_cvt_pk_bf16_f32 v242, v90, v98
	v_cvt_pk_bf16_f32 v243, v91, v99
	v_cvt_pk_bf16_f32 v244, v92, v100
	v_cvt_pk_bf16_f32 v245, v93, v101
	global_store_dwordx4 v129, v[242:245], s[78:79] offset:128
	v_add_f32_e32 v50, v50, v164
	v_add_f32_e32 v58, v58, v168
	v_add_f32_e32 v51, v51, v165
	v_add_f32_e32 v59, v59, v169
	v_add_f32_e32 v52, v52, v166
	v_add_f32_e32 v60, v60, v170
	v_add_f32_e32 v53, v53, v167
	v_add_f32_e32 v61, v61, v171
	v_mul_f32_e32 v50, 0xbfb8aa3b, v50
	v_mul_f32_e32 v58, 0xbfb8aa3b, v58
	v_mul_f32_e32 v51, 0xbfb8aa3b, v51
	v_mul_f32_e32 v59, 0xbfb8aa3b, v59
	v_mul_f32_e32 v52, 0xbfb8aa3b, v52
	v_mul_f32_e32 v60, 0xbfb8aa3b, v60
	v_mul_f32_e32 v53, 0xbfb8aa3b, v53
	v_mul_f32_e32 v61, 0xbfb8aa3b, v61
	v_exp_f32_e32 v50, v50
	v_exp_f32_e32 v58, v58
	v_exp_f32_e32 v51, v51
	v_exp_f32_e32 v59, v59
	v_exp_f32_e32 v52, v52
	v_exp_f32_e32 v60, v60
	v_exp_f32_e32 v53, v53
	v_exp_f32_e32 v61, v61
	v_add_f32_e32 v50, 1.0, v50
	v_add_f32_e32 v58, 1.0, v58
	v_add_f32_e32 v51, 1.0, v51
	v_add_f32_e32 v59, 1.0, v59
	v_add_f32_e32 v52, 1.0, v52
	v_add_f32_e32 v60, 1.0, v60
	v_add_f32_e32 v53, 1.0, v53
	v_add_f32_e32 v61, 1.0, v61
	v_rcp_f32_e32 v50, v50
	v_rcp_f32_e32 v58, v58
	v_rcp_f32_e32 v51, v51
	v_rcp_f32_e32 v59, v59
	v_rcp_f32_e32 v52, v52
	v_rcp_f32_e32 v60, v60
	v_rcp_f32_e32 v53, v53
	v_rcp_f32_e32 v61, v61
	v_mul_f32_e32 v82, 0xc1000000, v50
	v_mul_f32_e32 v83, 0xc1000000, v51
	v_mul_f32_e32 v84, 0xc1000000, v52
	v_mul_f32_e32 v85, 0xc1000000, v53
	v_mul_f32_e32 v82, v204, v82
	v_mul_f32_e32 v83, v205, v83
	v_mul_f32_e32 v84, v206, v84
; #define LAS __attribute__((address_space(3)))
; DI unsigned cvt_pk_bf16(float lo, float hi) { unsigned r; asm volatile("v_cvt_pk_bf16_f32 %0, %1, %2" : "=v"(r) : "v"(lo), "v"(hi)); return r; }
; DI float sigmoidf_(float x) { return __builtin_amdgcn_rcpf(1.f + __expf(-x)); }
; template <bool FIRST>
; DI void lru_tile2(const LruP& P, const float* cbuf, int hb, int row, int pos, int fr, int fq, LAS float* xcs) {
;     ...
;     for (int nt = 0; nt < 5; ++nt) {
;         const int cur = nt & 1;
;         if (nt < 4) LRU_PRELOAD(cur ^ 1, nt + 1);
;         f32x4 ar[2], ai[2];
;         ar[0] = (f32x4){0.f, 0.f, 0.f, 0.f}; ar[1] = ar[0]; ai[0] = ar[0]; ai[1] = ar[0];
; #pragma unroll
;         for (int ks = 0; ks < 3; ++ks)
; #pragma unroll
;             for (int tl = 0; tl < 2; ++tl) { ar[tl] = __builtin_amdgcn_mfma_f32_16x16x32_bf16(W[cur][ks], xf[tl][ks], ar[tl], 0, 0, 0); ai[tl] = __builtin_amdgcn_mfma_f32_16x16x32_bf16(W[cur][3 + ks], xf[tl][ks], ai[tl], 0, 0, 0); }
;         const int ch = 80 * hb + 16 * nt + 4 * fq; f32x4 av[2], bv[2], xc[2];
; #pragma unroll
;         for (int tl = 0; tl < 2; ++tl) xc[tl] = *(const LAS f32x4*)(xcs + (tl * 16 + fr) * XCP + 16 * nt + 4 * fq);
;         const f32x4 ga4 = C[cur][0], gx4 = C[cur][1], sp4 = C[cur][2];
; #pragma unroll
;         for (int tl = 0; tl < 2; ++tl)
; #pragma unroll
;             for (int e = 0; e < 4; ++e) {
;                 const float r = sigmoidf_(ar[tl][e] + ga4[e]), ig = sigmoidf_(ai[tl][e] + gx4[e]);
;                 const float la = -8.f * r * sp4[e]; const float a = __expf(la);
;                 av[tl][e] = (la > -0.03f) ? -la * (1.f + la * (0.5f + la * (0.16666667f + la * 0.041666668f))) : 1.f - a;
;                 const float t = 2.f * la; const float om = (t > -0.06f) ? -t * (1.f + t * (0.5f + t * (0.16666667f + t * 0.041666668f))) : 1.f - a * a;
;                 bv[tl][e] = __builtin_amdgcn_sqrtf(om) * (ig * xc[tl][e]); }
; #pragma unroll
;         for (int tl = 0; tl < 2; ++tl) { u32x4 w;
;             w.x = cvt_pk_bf16(av[tl][0], bv[tl][0]); w.y = cvt_pk_bf16(av[tl][1], bv[tl][1]); w.z = cvt_pk_bf16(av[tl][2], bv[tl][2]); w.w = cvt_pk_bf16(av[tl][3], bv[tl][3]);
;             *(u32x4*)((unsigned*)P.A + (size_t)(row + 16 * tl) * DRNN + ch) = w; } }
	v_mul_f32_e32 v85, v207, v85
	v_mul_f32_e32 v86, 0x3fb8aa3b, v82
	v_mul_f32_e32 v87, 0x3fb8aa3b, v83
	v_mul_f32_e32 v88, 0x3fb8aa3b, v84
	v_mul_f32_e32 v89, 0x3fb8aa3b, v85
	v_exp_f32_e32 v86, v86
	v_exp_f32_e32 v87, v87
	v_exp_f32_e32 v88, v88
	v_exp_f32_e32 v89, v89
	v_fmamk_f32 v90, v82, 0x3d2aaaab, v252
	v_fmamk_f32 v91, v83, 0x3d2aaaab, v252
	v_fmamk_f32 v92, v84, 0x3d2aaaab, v252
	v_fmamk_f32 v93, v85, 0x3d2aaaab, v252
	v_fma_f32 v90, v82, v90, 0.5
	v_fma_f32 v91, v83, v91, 0.5
	v_fma_f32 v92, v84, v92, 0.5
	v_fma_f32 v93, v85, v93, 0.5
	v_fma_f32 v90, v82, v90, 1.0
	v_fma_f32 v91, v83, v91, 1.0
	v_fma_f32 v92, v84, v92, 1.0
	v_fma_f32 v93, v85, v93, 1.0
	v_mul_f32_e64 v90, v90, -v82
	v_mul_f32_e64 v91, v91, -v83
	v_mul_f32_e64 v92, v92, -v84
	v_mul_f32_e64 v93, v93, -v85
	v_sub_f32_e32 v102, 1.0, v86
	v_sub_f32_e32 v103, 1.0, v87
	v_sub_f32_e32 v104, 1.0, v88
	v_sub_f32_e32 v105, 1.0, v89
	v_cmp_lt_f32_e32 vcc, s18, v82
	s_nop 1
	v_cndmask_b32_e32 v90, v102, v90, vcc
	v_cmp_lt_f32_e32 vcc, s18, v83
	s_nop 1
	v_cndmask_b32_e32 v91, v103, v91, vcc
	v_cmp_lt_f32_e32 vcc, s18, v84
	s_nop 1
	v_cndmask_b32_e32 v92, v104, v92, vcc
	v_cmp_lt_f32_e32 vcc, s18, v85
	s_nop 1
	v_cndmask_b32_e32 v93, v105, v93, vcc
	v_add_f32_e32 v106, v82, v82
	v_add_f32_e32 v107, v83, v83
	v_add_f32_e32 v108, v84, v84
	v_add_f32_e32 v109, v85, v85
	v_fmamk_f32 v98, v106, 0x3d2aaaab, v252
	v_fmamk_f32 v99, v107, 0x3d2aaaab, v252
	v_fmamk_f32 v100, v108, 0x3d2aaaab, v252
	v_fmamk_f32 v101, v109, 0x3d2aaaab, v252
	v_fma_f32 v98, v106, v98, 0.5
	v_fma_f32 v99, v107, v99, 0.5
	v_fma_f32 v100, v108, v100, 0.5
	v_fma_f32 v101, v109, v101, 0.5
	v_fma_f32 v98, v106, v98, 1.0
	v_fma_f32 v99, v107, v99, 1.0
	v_fma_f32 v100, v108, v100, 1.0
	v_fma_f32 v101, v109, v101, 1.0
	v_mul_f32_e64 v98, v98, -v106
	v_mul_f32_e64 v99, v99, -v107
	v_mul_f32_e64 v100, v100, -v108
	v_mul_f32_e64 v101, v101, -v109
	v_fma_f32 v102, -v86, v86, 1.0
	v_fma_f32 v103, -v87, v87, 1.0
	v_fma_f32 v104, -v88, v88, 1.0
	v_fma_f32 v105, -v89, v89, 1.0
	v_cmp_lt_f32_e32 vcc, s19, v106
	s_nop 1
	v_cndmask_b32_e32 v98, v102, v98, vcc
	v_cmp_lt_f32_e32 vcc, s19, v107
	s_nop 1
	v_cndmask_b32_e32 v99, v103, v99, vcc
	v_cmp_lt_f32_e32 vcc, s19, v108
	s_nop 1
	v_cndmask_b32_e32 v100, v104, v100, vcc
	v_cmp_lt_f32_e32 vcc, s19, v109
	s_nop 1
	v_cndmask_b32_e32 v101, v105, v101, vcc
	v_sqrt_f32_e32 v98, v98
	v_sqrt_f32_e32 v99, v99
	v_sqrt_f32_e32 v100, v100
	v_sqrt_f32_e32 v101, v101
	v_mul_f32_e32 v58, v58, v78
	v_mul_f32_e32 v59, v59, v79
	v_mul_f32_e32 v60, v60, v80
	v_mul_f32_e32 v61, v61, v81
	v_mul_f32_e32 v98, v98, v58
	v_mul_f32_e32 v99, v99, v59
	v_mul_f32_e32 v100, v100, v60
	v_mul_f32_e32 v101, v101, v61
	v_cvt_pk_bf16_f32 v248, v90, v98
	v_cvt_pk_bf16_f32 v249, v91, v99
	v_cvt_pk_bf16_f32 v250, v92, v100
	v_cvt_pk_bf16_f32 v251, v93, v101
	global_store_dwordx4 v130, v[248:251], s[78:79] offset:128
	global_load_dwordx4 v[140:143], v94, s[68:69] offset:0
	global_load_dwordx4 v[152:155], v96, s[68:69] offset:0
	global_load_dwordx4 v[144:147], v94, s[68:69] offset:64
	global_load_dwordx4 v[156:159], v96, s[68:69] offset:64
	global_load_dwordx4 v[148:151], v94, s[68:69] offset:128
	global_load_dwordx4 v[160:163], v96, s[68:69] offset:128
	global_load_dwordx4 v[164:167], v128, s[92:93] offset:256
	global_load_dwordx4 v[168:171], v128, s[96:97] offset:256
	global_load_dwordx4 v[204:207], v128, s[98:99] offset:256
	s_add_u32 s68, s68, 0xc00
	s_addc_u32 s69, s69, 0
	ds_read_b128 v[62:65], v237 offset:192
	ds_read_b128 v[78:81], v237 offset:5568
	s_waitcnt vmcnt(11)
	v_mfma_f32_16x16x32_bf16 v[42:45], v[180:183], v[2:5], 0
	v_mfma_f32_16x16x32_bf16 v[46:49], v[192:195], v[2:5], 0
	v_mfma_f32_16x16x32_bf16 v[50:53], v[180:183], v[30:33], 0
	v_mfma_f32_16x16x32_bf16 v[58:61], v[192:195], v[30:33], 0
	v_mfma_f32_16x16x32_bf16 v[42:45], v[184:187], v[6:9], v[42:45]
	v_mfma_f32_16x16x32_bf16 v[46:49], v[196:199], v[6:9], v[46:49]
	v_mfma_f32_16x16x32_bf16 v[50:53], v[184:187], v[34:37], v[50:53]
	v_mfma_f32_16x16x32_bf16 v[58:61], v[196:199], v[34:37], v[58:61]
	v_mfma_f32_16x16x32_bf16 v[42:45], v[188:191], v[22:25], v[42:45]
	v_mfma_f32_16x16x32_bf16 v[46:49], v[200:203], v[22:25], v[46:49]
	v_mfma_f32_16x16x32_bf16 v[50:53], v[188:191], v[38:41], v[50:53]
	v_mfma_f32_16x16x32_bf16 v[58:61], v[200:203], v[38:41], v[58:61]
	s_nop 7
	s_nop 1
	s_waitcnt lgkmcnt(0)
; #define LAS __attribute__((address_space(3)))
; DI unsigned cvt_pk_bf16(float lo, float hi) { unsigned r; asm volatile("v_cvt_pk_bf16_f32 %0, %1, %2" : "=v"(r) : "v"(lo), "v"(hi)); return r; }
; DI float sigmoidf_(float x) { return __builtin_amdgcn_rcpf(1.f + __expf(-x)); }
; template <bool FIRST>
; DI void lru_tile2(const LruP& P, const float* cbuf, int hb, int row, int pos, int fr, int fq, LAS float* xcs) {
;     ...
;         const int ch = 80 * hb + 16 * nt + 4 * fq; f32x4 av[2], bv[2], xc[2];
; #pragma unroll
;         for (int tl = 0; tl < 2; ++tl) xc[tl] = *(const LAS f32x4*)(xcs + (tl * 16 + fr) * XCP + 16 * nt + 4 * fq);
;         const f32x4 ga4 = C[cur][0], gx4 = C[cur][1], sp4 = C[cur][2];
; #pragma unroll
;         for (int tl = 0; tl < 2; ++tl)
; #pragma unroll
;             for (int e = 0; e < 4; ++e) {
;                 const float r = sigmoidf_(ar[tl][e] + ga4[e]), ig = sigmoidf_(ai[tl][e] + gx4[e]);
;                 const float la = -8.f * r * sp4[e]; const float a = __expf(la);
;                 av[tl][e] = (la > -0.03f) ? -la * (1.f + la * (0.5f + la * (0.16666667f + la * 0.041666668f))) : 1.f - a;
;                 const float t = 2.f * la; const float om = (t > -0.06f) ? -t * (1.f + t * (0.5f + t * (0.16666667f + t * 0.041666668f))) : 1.f - a * a;
;                 bv[tl][e] = __builtin_amdgcn_sqrtf(om) * (ig * xc[tl][e]); }
; #pragma unroll
;         for (int tl = 0; tl < 2; ++tl) { u32x4 w;
;             w.x = cvt_pk_bf16(av[tl][0], bv[tl][0]); w.y = cvt_pk_bf16(av[tl][1], bv[tl][1]); w.z = cvt_pk_bf16(av[tl][2], bv[tl][2]); w.w = cvt_pk_bf16(av[tl][3], bv[tl][3]);
;             *(u32x4*)((unsigned*)P.A + (size_t)(row + 16 * tl) * DRNN + ch) = w; } }
	v_add_f32_e32 v42, v42, v208
	v_add_f32_e32 v46, v46, v212
	v_add_f32_e32 v43, v43, v209
	v_add_f32_e32 v47, v47, v213
	v_add_f32_e32 v44, v44, v210
	v_add_f32_e32 v48, v48, v214
	v_add_f32_e32 v45, v45, v211
	v_add_f32_e32 v49, v49, v215
	v_mul_f32_e32 v42, 0xbfb8aa3b, v42
	v_mul_f32_e32 v46, 0xbfb8aa3b, v46
	v_mul_f32_e32 v43, 0xbfb8aa3b, v43
	v_mul_f32_e32 v47, 0xbfb8aa3b, v47
	v_mul_f32_e32 v44, 0xbfb8aa3b, v44
	v_mul_f32_e32 v48, 0xbfb8aa3b, v48
	v_mul_f32_e32 v45, 0xbfb8aa3b, v45
	v_mul_f32_e32 v49, 0xbfb8aa3b, v49
	v_exp_f32_e32 v42, v42
	v_exp_f32_e32 v46, v46
	v_exp_f32_e32 v43, v43
	v_exp_f32_e32 v47, v47
	v_exp_f32_e32 v44, v44
	v_exp_f32_e32 v48, v48
	v_exp_f32_e32 v45, v45
	v_exp_f32_e32 v49, v49
	v_add_f32_e32 v42, 1.0, v42
	v_add_f32_e32 v46, 1.0, v46
	v_add_f32_e32 v43, 1.0, v43
	v_add_f32_e32 v47, 1.0, v47
	v_add_f32_e32 v44, 1.0, v44
	v_add_f32_e32 v48, 1.0, v48
	v_add_f32_e32 v45, 1.0, v45
	v_add_f32_e32 v49, 1.0, v49
	v_rcp_f32_e32 v42, v42
	v_rcp_f32_e32 v46, v46
	v_rcp_f32_e32 v43, v43
	v_rcp_f32_e32 v47, v47
	v_rcp_f32_e32 v44, v44
	v_rcp_f32_e32 v48, v48
	v_rcp_f32_e32 v45, v45
	v_rcp_f32_e32 v49, v49
	v_mul_f32_e32 v82, 0xc1000000, v42
	v_mul_f32_e32 v83, 0xc1000000, v43
	v_mul_f32_e32 v84, 0xc1000000, v44
	v_mul_f32_e32 v85, 0xc1000000, v45
	v_mul_f32_e32 v82, v238, v82
	v_mul_f32_e32 v83, v239, v83
	v_mul_f32_e32 v84, v240, v84
	v_mul_f32_e32 v85, v241, v85
	v_mul_f32_e32 v86, 0x3fb8aa3b, v82
	v_mul_f32_e32 v87, 0x3fb8aa3b, v83
	v_mul_f32_e32 v88, 0x3fb8aa3b, v84
	v_mul_f32_e32 v89, 0x3fb8aa3b, v85
	v_exp_f32_e32 v86, v86
	v_exp_f32_e32 v87, v87
	v_exp_f32_e32 v88, v88
	v_exp_f32_e32 v89, v89
	v_fmamk_f32 v90, v82, 0x3d2aaaab, v252
	v_fmamk_f32 v91, v83, 0x3d2aaaab, v252
	v_fmamk_f32 v92, v84, 0x3d2aaaab, v252
	v_fmamk_f32 v93, v85, 0x3d2aaaab, v252
	v_fma_f32 v90, v82, v90, 0.5
	v_fma_f32 v91, v83, v91, 0.5
	v_fma_f32 v92, v84, v92, 0.5
	v_fma_f32 v93, v85, v93, 0.5
	v_fma_f32 v90, v82, v90, 1.0
	v_fma_f32 v91, v83, v91, 1.0
	v_fma_f32 v92, v84, v92, 1.0
	v_fma_f32 v93, v85, v93, 1.0
	v_mul_f32_e64 v90, v90, -v82
	v_mul_f32_e64 v91, v91, -v83
	v_mul_f32_e64 v92, v92, -v84
	v_mul_f32_e64 v93, v93, -v85
	v_sub_f32_e32 v102, 1.0, v86
	v_sub_f32_e32 v103, 1.0, v87
	v_sub_f32_e32 v104, 1.0, v88
	v_sub_f32_e32 v105, 1.0, v89
	v_cmp_lt_f32_e32 vcc, s18, v82
	s_nop 1
	v_cndmask_b32_e32 v90, v102, v90, vcc
	v_cmp_lt_f32_e32 vcc, s18, v83
	s_nop 1
	v_cndmask_b32_e32 v91, v103, v91, vcc
	v_cmp_lt_f32_e32 vcc, s18, v84
	s_nop 1
	v_cndmask_b32_e32 v92, v104, v92, vcc
	v_cmp_lt_f32_e32 vcc, s18, v85
	s_nop 1
	v_cndmask_b32_e32 v93, v105, v93, vcc
	v_add_f32_e32 v106, v82, v82
	v_add_f32_e32 v107, v83, v83
	v_add_f32_e32 v108, v84, v84
	v_add_f32_e32 v109, v85, v85
	v_fmamk_f32 v98, v106, 0x3d2aaaab, v252
	v_fmamk_f32 v99, v107, 0x3d2aaaab, v252
	v_fmamk_f32 v100, v108, 0x3d2aaaab, v252
	v_fmamk_f32 v101, v109, 0x3d2aaaab, v252
	v_fma_f32 v98, v106, v98, 0.5
	v_fma_f32 v99, v107, v99, 0.5
	v_fma_f32 v100, v108, v100, 0.5
	v_fma_f32 v101, v109, v101, 0.5
	v_fma_f32 v98, v106, v98, 1.0
	v_fma_f32 v99, v107, v99, 1.0
	v_fma_f32 v100, v108, v100, 1.0
	v_fma_f32 v101, v109, v101, 1.0
	v_mul_f32_e64 v98, v98, -v106
	v_mul_f32_e64 v99, v99, -v107
	v_mul_f32_e64 v100, v100, -v108
	v_mul_f32_e64 v101, v101, -v109
	v_fma_f32 v102, -v86, v86, 1.0
	v_fma_f32 v103, -v87, v87, 1.0
	v_fma_f32 v104, -v88, v88, 1.0
	v_fma_f32 v105, -v89, v89, 1.0
	v_cmp_lt_f32_e32 vcc, s19, v106
	s_nop 1
	v_cndmask_b32_e32 v98, v102, v98, vcc
	v_cmp_lt_f32_e32 vcc, s19, v107
	s_nop 1
	v_cndmask_b32_e32 v99, v103, v99, vcc
	v_cmp_lt_f32_e32 vcc, s19, v108
	s_nop 1
	v_cndmask_b32_e32 v100, v104, v100, vcc
	v_cmp_lt_f32_e32 vcc, s19, v109
	s_nop 1
	v_cndmask_b32_e32 v101, v105, v101, vcc
	v_sqrt_f32_e32 v98, v98
	v_sqrt_f32_e32 v99, v99
	v_sqrt_f32_e32 v100, v100
	v_sqrt_f32_e32 v101, v101
	v_mul_f32_e32 v46, v46, v62
	v_mul_f32_e32 v47, v47, v63
	v_mul_f32_e32 v48, v48, v64
	v_mul_f32_e32 v49, v49, v65
	v_mul_f32_e32 v98, v98, v46
	v_mul_f32_e32 v99, v99, v47
	v_mul_f32_e32 v100, v100, v48
	v_mul_f32_e32 v101, v101, v49
	v_cvt_pk_bf16_f32 v242, v90, v98
	v_cvt_pk_bf16_f32 v243, v91, v99
	v_cvt_pk_bf16_f32 v244, v92, v100
	v_cvt_pk_bf16_f32 v245, v93, v101
	global_store_dwordx4 v129, v[242:245], s[78:79] offset:192
	v_add_f32_e32 v50, v50, v208
	v_add_f32_e32 v58, v58, v212
	v_add_f32_e32 v51, v51, v209
	v_add_f32_e32 v59, v59, v213
	v_add_f32_e32 v52, v52, v210
	v_add_f32_e32 v60, v60, v214
	v_add_f32_e32 v53, v53, v211
	v_add_f32_e32 v61, v61, v215
	v_mul_f32_e32 v50, 0xbfb8aa3b, v50
	v_mul_f32_e32 v58, 0xbfb8aa3b, v58
	v_mul_f32_e32 v51, 0xbfb8aa3b, v51
	v_mul_f32_e32 v59, 0xbfb8aa3b, v59
	v_mul_f32_e32 v52, 0xbfb8aa3b, v52
	v_mul_f32_e32 v60, 0xbfb8aa3b, v60
	v_mul_f32_e32 v53, 0xbfb8aa3b, v53
	v_mul_f32_e32 v61, 0xbfb8aa3b, v61
	v_exp_f32_e32 v50, v50
	v_exp_f32_e32 v58, v58
	v_exp_f32_e32 v51, v51
	v_exp_f32_e32 v59, v59
	v_exp_f32_e32 v52, v52
	v_exp_f32_e32 v60, v60
	v_exp_f32_e32 v53, v53
	v_exp_f32_e32 v61, v61
	v_add_f32_e32 v50, 1.0, v50
	v_add_f32_e32 v58, 1.0, v58
	v_add_f32_e32 v51, 1.0, v51
	v_add_f32_e32 v59, 1.0, v59
	v_add_f32_e32 v52, 1.0, v52
	v_add_f32_e32 v60, 1.0, v60
	v_add_f32_e32 v53, 1.0, v53
	v_add_f32_e32 v61, 1.0, v61
	v_rcp_f32_e32 v50, v50
	v_rcp_f32_e32 v58, v58
	v_rcp_f32_e32 v51, v51
	v_rcp_f32_e32 v59, v59
	v_rcp_f32_e32 v52, v52
	v_rcp_f32_e32 v60, v60
	v_rcp_f32_e32 v53, v53
	v_rcp_f32_e32 v61, v61
	v_mul_f32_e32 v82, 0xc1000000, v50
	v_mul_f32_e32 v83, 0xc1000000, v51
	v_mul_f32_e32 v84, 0xc1000000, v52
	v_mul_f32_e32 v85, 0xc1000000, v53
	v_mul_f32_e32 v82, v238, v82
	v_mul_f32_e32 v83, v239, v83
	v_mul_f32_e32 v84, v240, v84
; #define LAS __attribute__((address_space(3)))
; DI unsigned cvt_pk_bf16(float lo, float hi) { unsigned r; asm volatile("v_cvt_pk_bf16_f32 %0, %1, %2" : "=v"(r) : "v"(lo), "v"(hi)); return r; }
; DI float sigmoidf_(float x) { return __builtin_amdgcn_rcpf(1.f + __expf(-x)); }
; template <bool FIRST>
; DI void lru_tile2(const LruP& P, const float* cbuf, int hb, int row, int pos, int fr, int fq, LAS float* xcs) {
;     ...
;     for (int nt = 0; nt < 5; ++nt) {
;         const int cur = nt & 1;
;         if (nt < 4) LRU_PRELOAD(cur ^ 1, nt + 1);
;         f32x4 ar[2], ai[2];
;         ar[0] = (f32x4){0.f, 0.f, 0.f, 0.f}; ar[1] = ar[0]; ai[0] = ar[0]; ai[1] = ar[0];
; #pragma unroll
;         for (int ks = 0; ks < 3; ++ks)
; #pragma unroll
;             for (int tl = 0; tl < 2; ++tl) { ar[tl] = __builtin_amdgcn_mfma_f32_16x16x32_bf16(W[cur][ks], xf[tl][ks], ar[tl], 0, 0, 0); ai[tl] = __builtin_amdgcn_mfma_f32_16x16x32_bf16(W[cur][3 + ks], xf[tl][ks], ai[tl], 0, 0, 0); }
;         const int ch = 80 * hb + 16 * nt + 4 * fq; f32x4 av[2], bv[2], xc[2];
; #pragma unroll
;         for (int tl = 0; tl < 2; ++tl) xc[tl] = *(const LAS f32x4*)(xcs + (tl * 16 + fr) * XCP + 16 * nt + 4 * fq);
;         const f32x4 ga4 = C[cur][0], gx4 = C[cur][1], sp4 = C[cur][2];
; #pragma unroll
;         for (int tl = 0; tl < 2; ++tl)
; #pragma unroll
;             for (int e = 0; e < 4; ++e) {
;                 const float r = sigmoidf_(ar[tl][e] + ga4[e]), ig = sigmoidf_(ai[tl][e] + gx4[e]);
;                 const float la = -8.f * r * sp4[e]; const float a = __expf(la);
;                 av[tl][e] = (la > -0.03f) ? -la * (1.f + la * (0.5f + la * (0.16666667f + la * 0.041666668f))) : 1.f - a;
;                 const float t = 2.f * la; const float om = (t > -0.06f) ? -t * (1.f + t * (0.5f + t * (0.16666667f + t * 0.041666668f))) : 1.f - a * a;
;                 bv[tl][e] = __builtin_amdgcn_sqrtf(om) * (ig * xc[tl][e]); }
; #pragma unroll
;         for (int tl = 0; tl < 2; ++tl) { u32x4 w;
;             w.x = cvt_pk_bf16(av[tl][0], bv[tl][0]); w.y = cvt_pk_bf16(av[tl][1], bv[tl][1]); w.z = cvt_pk_bf16(av[tl][2], bv[tl][2]); w.w = cvt_pk_bf16(av[tl][3], bv[tl][3]);
;             *(u32x4*)((unsigned*)P.A + (size_t)(row + 16 * tl) * DRNN + ch) = w; } }
	v_mul_f32_e32 v85, v241, v85
	v_mul_f32_e32 v86, 0x3fb8aa3b, v82
	v_mul_f32_e32 v87, 0x3fb8aa3b, v83
	v_mul_f32_e32 v88, 0x3fb8aa3b, v84
	v_mul_f32_e32 v89, 0x3fb8aa3b, v85
	v_exp_f32_e32 v86, v86
	v_exp_f32_e32 v87, v87
	v_exp_f32_e32 v88, v88
	v_exp_f32_e32 v89, v89
	v_fmamk_f32 v90, v82, 0x3d2aaaab, v252
	v_fmamk_f32 v91, v83, 0x3d2aaaab, v252
	v_fmamk_f32 v92, v84, 0x3d2aaaab, v252
	v_fmamk_f32 v93, v85, 0x3d2aaaab, v252
	v_fma_f32 v90, v82, v90, 0.5
	v_fma_f32 v91, v83, v91, 0.5
	v_fma_f32 v92, v84, v92, 0.5
	v_fma_f32 v93, v85, v93, 0.5
	v_fma_f32 v90, v82, v90, 1.0
	v_fma_f32 v91, v83, v91, 1.0
	v_fma_f32 v92, v84, v92, 1.0
	v_fma_f32 v93, v85, v93, 1.0
	v_mul_f32_e64 v90, v90, -v82
	v_mul_f32_e64 v91, v91, -v83
	v_mul_f32_e64 v92, v92, -v84
	v_mul_f32_e64 v93, v93, -v85
	v_sub_f32_e32 v102, 1.0, v86
	v_sub_f32_e32 v103, 1.0, v87
	v_sub_f32_e32 v104, 1.0, v88
	v_sub_f32_e32 v105, 1.0, v89
	v_cmp_lt_f32_e32 vcc, s18, v82
	s_nop 1
	v_cndmask_b32_e32 v90, v102, v90, vcc
	v_cmp_lt_f32_e32 vcc, s18, v83
	s_nop 1
	v_cndmask_b32_e32 v91, v103, v91, vcc
	v_cmp_lt_f32_e32 vcc, s18, v84
	s_nop 1
	v_cndmask_b32_e32 v92, v104, v92, vcc
	v_cmp_lt_f32_e32 vcc, s18, v85
	s_nop 1
	v_cndmask_b32_e32 v93, v105, v93, vcc
	v_add_f32_e32 v106, v82, v82
	v_add_f32_e32 v107, v83, v83
	v_add_f32_e32 v108, v84, v84
	v_add_f32_e32 v109, v85, v85
	v_fmamk_f32 v98, v106, 0x3d2aaaab, v252
	v_fmamk_f32 v99, v107, 0x3d2aaaab, v252
	v_fmamk_f32 v100, v108, 0x3d2aaaab, v252
	v_fmamk_f32 v101, v109, 0x3d2aaaab, v252
	v_fma_f32 v98, v106, v98, 0.5
	v_fma_f32 v99, v107, v99, 0.5
	v_fma_f32 v100, v108, v100, 0.5
	v_fma_f32 v101, v109, v101, 0.5
	v_fma_f32 v98, v106, v98, 1.0
	v_fma_f32 v99, v107, v99, 1.0
	v_fma_f32 v100, v108, v100, 1.0
	v_fma_f32 v101, v109, v101, 1.0
	v_mul_f32_e64 v98, v98, -v106
	v_mul_f32_e64 v99, v99, -v107
	v_mul_f32_e64 v100, v100, -v108
	v_mul_f32_e64 v101, v101, -v109
	v_fma_f32 v102, -v86, v86, 1.0
	v_fma_f32 v103, -v87, v87, 1.0
	v_fma_f32 v104, -v88, v88, 1.0
	v_fma_f32 v105, -v89, v89, 1.0
	v_cmp_lt_f32_e32 vcc, s19, v106
	s_nop 1
	v_cndmask_b32_e32 v98, v102, v98, vcc
	v_cmp_lt_f32_e32 vcc, s19, v107
	s_nop 1
	v_cndmask_b32_e32 v99, v103, v99, vcc
	v_cmp_lt_f32_e32 vcc, s19, v108
	s_nop 1
	v_cndmask_b32_e32 v100, v104, v100, vcc
	v_cmp_lt_f32_e32 vcc, s19, v109
	s_nop 1
	v_cndmask_b32_e32 v101, v105, v101, vcc
	v_sqrt_f32_e32 v98, v98
	v_sqrt_f32_e32 v99, v99
	v_sqrt_f32_e32 v100, v100
	v_sqrt_f32_e32 v101, v101
	v_mul_f32_e32 v58, v58, v78
	v_mul_f32_e32 v59, v59, v79
	v_mul_f32_e32 v60, v60, v80
	v_mul_f32_e32 v61, v61, v81
	v_mul_f32_e32 v98, v98, v58
	v_mul_f32_e32 v99, v99, v59
	v_mul_f32_e32 v100, v100, v60
	v_mul_f32_e32 v101, v101, v61
	v_cvt_pk_bf16_f32 v248, v90, v98
	v_cvt_pk_bf16_f32 v249, v91, v99
	v_cvt_pk_bf16_f32 v250, v92, v100
	v_cvt_pk_bf16_f32 v251, v93, v101
	global_store_dwordx4 v130, v[248:251], s[78:79] offset:192
	ds_read_b128 v[62:65], v237 offset:256
	ds_read_b128 v[78:81], v237 offset:5632
	s_waitcnt vmcnt(2)
	v_mfma_f32_16x16x32_bf16 v[42:45], v[140:143], v[2:5], 0
	v_mfma_f32_16x16x32_bf16 v[46:49], v[152:155], v[2:5], 0
	v_mfma_f32_16x16x32_bf16 v[50:53], v[140:143], v[30:33], 0
	v_mfma_f32_16x16x32_bf16 v[58:61], v[152:155], v[30:33], 0
	v_mfma_f32_16x16x32_bf16 v[42:45], v[144:147], v[6:9], v[42:45]
	v_mfma_f32_16x16x32_bf16 v[46:49], v[156:159], v[6:9], v[46:49]
	v_mfma_f32_16x16x32_bf16 v[50:53], v[144:147], v[34:37], v[50:53]
	v_mfma_f32_16x16x32_bf16 v[58:61], v[156:159], v[34:37], v[58:61]
	v_mfma_f32_16x16x32_bf16 v[42:45], v[148:151], v[22:25], v[42:45]
	v_mfma_f32_16x16x32_bf16 v[46:49], v[160:163], v[22:25], v[46:49]
	v_mfma_f32_16x16x32_bf16 v[50:53], v[148:151], v[38:41], v[50:53]
	v_mfma_f32_16x16x32_bf16 v[58:61], v[160:163], v[38:41], v[58:61]
	s_nop 7
	s_nop 1
	s_waitcnt lgkmcnt(0)
	v_add_f32_e32 v42, v42, v164
	v_add_f32_e32 v46, v46, v168
	v_add_f32_e32 v43, v43, v165
	v_add_f32_e32 v47, v47, v169
	v_add_f32_e32 v44, v44, v166
	v_add_f32_e32 v48, v48, v170
	v_add_f32_e32 v45, v45, v167
	v_add_f32_e32 v49, v49, v171
	v_mul_f32_e32 v42, 0xbfb8aa3b, v42
	v_mul_f32_e32 v46, 0xbfb8aa3b, v46
	v_mul_f32_e32 v43, 0xbfb8aa3b, v43
	v_mul_f32_e32 v47, 0xbfb8aa3b, v47
	v_mul_f32_e32 v44, 0xbfb8aa3b, v44
	v_mul_f32_e32 v48, 0xbfb8aa3b, v48
	v_mul_f32_e32 v45, 0xbfb8aa3b, v45
	v_mul_f32_e32 v49, 0xbfb8aa3b, v49
	v_exp_f32_e32 v42, v42
	v_exp_f32_e32 v46, v46
	v_exp_f32_e32 v43, v43
	v_exp_f32_e32 v47, v47
	v_exp_f32_e32 v44, v44
	v_exp_f32_e32 v48, v48
	v_exp_f32_e32 v45, v45
	v_exp_f32_e32 v49, v49
	v_add_f32_e32 v42, 1.0, v42
	v_add_f32_e32 v46, 1.0, v46
	v_add_f32_e32 v43, 1.0, v43
	v_add_f32_e32 v47, 1.0, v47
	v_add_f32_e32 v44, 1.0, v44
	v_add_f32_e32 v48, 1.0, v48
	v_add_f32_e32 v45, 1.0, v45
	v_add_f32_e32 v49, 1.0, v49
	v_rcp_f32_e32 v42, v42
	v_rcp_f32_e32 v46, v46
	v_rcp_f32_e32 v43, v43
	v_rcp_f32_e32 v47, v47
	v_rcp_f32_e32 v44, v44
	v_rcp_f32_e32 v48, v48
	v_rcp_f32_e32 v45, v45
	v_rcp_f32_e32 v49, v49
	v_mul_f32_e32 v82, 0xc1000000, v42
	v_mul_f32_e32 v83, 0xc1000000, v43
	v_mul_f32_e32 v84, 0xc1000000, v44
	v_mul_f32_e32 v85, 0xc1000000, v45
	v_mul_f32_e32 v82, v204, v82
	v_mul_f32_e32 v83, v205, v83
	v_mul_f32_e32 v84, v206, v84
	v_mul_f32_e32 v85, v207, v85
	v_mul_f32_e32 v86, 0x3fb8aa3b, v82
	v_mul_f32_e32 v87, 0x3fb8aa3b, v83
	v_mul_f32_e32 v88, 0x3fb8aa3b, v84
	v_mul_f32_e32 v89, 0x3fb8aa3b, v85
	v_exp_f32_e32 v86, v86
	v_exp_f32_e32 v87, v87
	v_exp_f32_e32 v88, v88
	v_exp_f32_e32 v89, v89
	v_fmamk_f32 v90, v82, 0x3d2aaaab, v252
	v_fmamk_f32 v91, v83, 0x3d2aaaab, v252
	v_fmamk_f32 v92, v84, 0x3d2aaaab, v252
	v_fmamk_f32 v93, v85, 0x3d2aaaab, v252
	v_fma_f32 v90, v82, v90, 0.5
; #define LAS __attribute__((address_space(3)))
; DI unsigned cvt_pk_bf16(float lo, float hi) { unsigned r; asm volatile("v_cvt_pk_bf16_f32 %0, %1, %2" : "=v"(r) : "v"(lo), "v"(hi)); return r; }
; DI float sigmoidf_(float x) { return __builtin_amdgcn_rcpf(1.f + __expf(-x)); }
; template <bool FIRST>
; DI void lru_tile2(const LruP& P, const float* cbuf, int hb, int row, int pos, int fr, int fq, LAS float* xcs) {
;     ...
;         const int ch = 80 * hb + 16 * nt + 4 * fq; f32x4 av[2], bv[2], xc[2];
; #pragma unroll
;         for (int tl = 0; tl < 2; ++tl) xc[tl] = *(const LAS f32x4*)(xcs + (tl * 16 + fr) * XCP + 16 * nt + 4 * fq);
;         const f32x4 ga4 = C[cur][0], gx4 = C[cur][1], sp4 = C[cur][2];
; #pragma unroll
;         for (int tl = 0; tl < 2; ++tl)
; #pragma unroll
;             for (int e = 0; e < 4; ++e) {
;                 const float r = sigmoidf_(ar[tl][e] + ga4[e]), ig = sigmoidf_(ai[tl][e] + gx4[e]);
;                 const float la = -8.f * r * sp4[e]; const float a = __expf(la);
;                 av[tl][e] = (la > -0.03f) ? -la * (1.f + la * (0.5f + la * (0.16666667f + la * 0.041666668f))) : 1.f - a;
;                 const float t = 2.f * la; const float om = (t > -0.06f) ? -t * (1.f + t * (0.5f + t * (0.16666667f + t * 0.041666668f))) : 1.f - a * a;
;                 bv[tl][e] = __builtin_amdgcn_sqrtf(om) * (ig * xc[tl][e]); }
; #pragma unroll
;         for (int tl = 0; tl < 2; ++tl) { u32x4 w;
;             w.x = cvt_pk_bf16(av[tl][0], bv[tl][0]); w.y = cvt_pk_bf16(av[tl][1], bv[tl][1]); w.z = cvt_pk_bf16(av[tl][2], bv[tl][2]); w.w = cvt_pk_bf16(av[tl][3], bv[tl][3]);
;             *(u32x4*)((unsigned*)P.A + (size_t)(row + 16 * tl) * DRNN + ch) = w; } }
; DI void phase_lru_gates(const Frame& F, int j) {
;     ...
;     for (int task = F.gw; task < (NT / 32) * 16; task += F.NGW) {
;         asm volatile("" ::: "memory");
;         const int hb = task & 15, tp = task >> 4; const int row = tp * 32 + fr; const int seq = seq_of_row(row), pos = pos_of_row(row);
;         const bool first = pos_of_row(tp * 32) == 0;
;         if (first) { const float* cbuf = row < NP ? nullptr : cst + ((size_t)j * 8 + (seq - 2)) * 3 * DRNN; lru_tile2<true>(P, cbuf, hb, row, pos, fr, fq, xcs); }
;         else lru_tile2<false>(P, nullptr, hb, row, pos, fr, fq, xcs);
;     }
	v_fma_f32 v91, v83, v91, 0.5
	v_fma_f32 v92, v84, v92, 0.5
	v_fma_f32 v93, v85, v93, 0.5
	v_fma_f32 v90, v82, v90, 1.0
	v_fma_f32 v91, v83, v91, 1.0
	v_fma_f32 v92, v84, v92, 1.0
	v_fma_f32 v93, v85, v93, 1.0
	v_mul_f32_e64 v90, v90, -v82
	v_mul_f32_e64 v91, v91, -v83
	v_mul_f32_e64 v92, v92, -v84
	v_mul_f32_e64 v93, v93, -v85
	v_sub_f32_e32 v102, 1.0, v86
	v_sub_f32_e32 v103, 1.0, v87
	v_sub_f32_e32 v104, 1.0, v88
	v_sub_f32_e32 v105, 1.0, v89
	v_cmp_lt_f32_e32 vcc, s18, v82
	s_nop 1
	v_cndmask_b32_e32 v90, v102, v90, vcc
	v_cmp_lt_f32_e32 vcc, s18, v83
	s_nop 1
	v_cndmask_b32_e32 v91, v103, v91, vcc
	v_cmp_lt_f32_e32 vcc, s18, v84
	s_nop 1
	v_cndmask_b32_e32 v92, v104, v92, vcc
	v_cmp_lt_f32_e32 vcc, s18, v85
	s_nop 1
	v_cndmask_b32_e32 v93, v105, v93, vcc
	v_add_f32_e32 v106, v82, v82
	v_add_f32_e32 v107, v83, v83
	v_add_f32_e32 v108, v84, v84
	v_add_f32_e32 v109, v85, v85
	v_fmamk_f32 v98, v106, 0x3d2aaaab, v252
	v_fmamk_f32 v99, v107, 0x3d2aaaab, v252
	v_fmamk_f32 v100, v108, 0x3d2aaaab, v252
	v_fmamk_f32 v101, v109, 0x3d2aaaab, v252
	v_fma_f32 v98, v106, v98, 0.5
	v_fma_f32 v99, v107, v99, 0.5
	v_fma_f32 v100, v108, v100, 0.5
	v_fma_f32 v101, v109, v101, 0.5
	v_fma_f32 v98, v106, v98, 1.0
	v_fma_f32 v99, v107, v99, 1.0
	v_fma_f32 v100, v108, v100, 1.0
	v_fma_f32 v101, v109, v101, 1.0
	v_mul_f32_e64 v98, v98, -v106
	v_mul_f32_e64 v99, v99, -v107
	v_mul_f32_e64 v100, v100, -v108
	v_mul_f32_e64 v101, v101, -v109
	v_fma_f32 v102, -v86, v86, 1.0
	v_fma_f32 v103, -v87, v87, 1.0
	v_fma_f32 v104, -v88, v88, 1.0
	v_fma_f32 v105, -v89, v89, 1.0
	v_cmp_lt_f32_e32 vcc, s19, v106
	s_nop 1
	v_cndmask_b32_e32 v98, v102, v98, vcc
	v_cmp_lt_f32_e32 vcc, s19, v107
	s_nop 1
	v_cndmask_b32_e32 v99, v103, v99, vcc
	v_cmp_lt_f32_e32 vcc, s19, v108
	s_nop 1
	v_cndmask_b32_e32 v100, v104, v100, vcc
	v_cmp_lt_f32_e32 vcc, s19, v109
	s_nop 1
	v_cndmask_b32_e32 v101, v105, v101, vcc
	v_sqrt_f32_e32 v98, v98
	v_sqrt_f32_e32 v99, v99
	v_sqrt_f32_e32 v100, v100
	v_sqrt_f32_e32 v101, v101
	v_mul_f32_e32 v46, v46, v62
	v_mul_f32_e32 v47, v47, v63
	v_mul_f32_e32 v48, v48, v64
	v_mul_f32_e32 v49, v49, v65
	v_mul_f32_e32 v98, v98, v46
	v_mul_f32_e32 v99, v99, v47
	v_mul_f32_e32 v100, v100, v48
	v_mul_f32_e32 v101, v101, v49
	v_cvt_pk_bf16_f32 v242, v90, v98
	v_cvt_pk_bf16_f32 v243, v91, v99
	v_cvt_pk_bf16_f32 v244, v92, v100
	v_cvt_pk_bf16_f32 v245, v93, v101
	global_store_dwordx4 v129, v[242:245], s[78:79] offset:256
	v_add_f32_e32 v50, v50, v164
	v_add_f32_e32 v58, v58, v168
	v_add_f32_e32 v51, v51, v165
	v_add_f32_e32 v59, v59, v169
	v_add_f32_e32 v52, v52, v166
	v_add_f32_e32 v60, v60, v170
	v_add_f32_e32 v53, v53, v167
	v_add_f32_e32 v61, v61, v171
	v_mul_f32_e32 v50, 0xbfb8aa3b, v50
	v_mul_f32_e32 v58, 0xbfb8aa3b, v58
	v_mul_f32_e32 v51, 0xbfb8aa3b, v51
	v_mul_f32_e32 v59, 0xbfb8aa3b, v59
	v_mul_f32_e32 v52, 0xbfb8aa3b, v52
	v_mul_f32_e32 v60, 0xbfb8aa3b, v60
	v_mul_f32_e32 v53, 0xbfb8aa3b, v53
	v_mul_f32_e32 v61, 0xbfb8aa3b, v61
	v_exp_f32_e32 v50, v50
	v_exp_f32_e32 v58, v58
	v_exp_f32_e32 v51, v51
	v_exp_f32_e32 v59, v59
	v_exp_f32_e32 v52, v52
	v_exp_f32_e32 v60, v60
	v_exp_f32_e32 v53, v53
	v_exp_f32_e32 v61, v61
	v_add_f32_e32 v50, 1.0, v50
	v_add_f32_e32 v58, 1.0, v58
	v_add_f32_e32 v51, 1.0, v51
	v_add_f32_e32 v59, 1.0, v59
	v_add_f32_e32 v52, 1.0, v52
	v_add_f32_e32 v60, 1.0, v60
	v_add_f32_e32 v53, 1.0, v53
	v_add_f32_e32 v61, 1.0, v61
	v_rcp_f32_e32 v50, v50
	v_rcp_f32_e32 v58, v58
	v_rcp_f32_e32 v51, v51
	v_rcp_f32_e32 v59, v59
	v_rcp_f32_e32 v52, v52
	v_rcp_f32_e32 v60, v60
	v_rcp_f32_e32 v53, v53
	v_rcp_f32_e32 v61, v61
	v_mul_f32_e32 v82, 0xc1000000, v50
	v_mul_f32_e32 v83, 0xc1000000, v51
	v_mul_f32_e32 v84, 0xc1000000, v52
	v_mul_f32_e32 v85, 0xc1000000, v53
	v_mul_f32_e32 v82, v204, v82
	v_mul_f32_e32 v83, v205, v83
	v_mul_f32_e32 v84, v206, v84
	v_mul_f32_e32 v85, v207, v85
	v_mul_f32_e32 v86, 0x3fb8aa3b, v82
	v_mul_f32_e32 v87, 0x3fb8aa3b, v83
	v_mul_f32_e32 v88, 0x3fb8aa3b, v84
	v_mul_f32_e32 v89, 0x3fb8aa3b, v85
	v_exp_f32_e32 v86, v86
	v_exp_f32_e32 v87, v87
	v_exp_f32_e32 v88, v88
	v_exp_f32_e32 v89, v89
	v_fmamk_f32 v90, v82, 0x3d2aaaab, v252
	v_fmamk_f32 v91, v83, 0x3d2aaaab, v252
	v_fmamk_f32 v92, v84, 0x3d2aaaab, v252
	v_fmamk_f32 v93, v85, 0x3d2aaaab, v252
	v_fma_f32 v90, v82, v90, 0.5
	v_fma_f32 v91, v83, v91, 0.5
	v_fma_f32 v92, v84, v92, 0.5
	v_fma_f32 v93, v85, v93, 0.5
	v_fma_f32 v90, v82, v90, 1.0
	v_fma_f32 v91, v83, v91, 1.0
	v_fma_f32 v92, v84, v92, 1.0
	v_fma_f32 v93, v85, v93, 1.0
	v_mul_f32_e64 v90, v90, -v82
	v_mul_f32_e64 v91, v91, -v83
	v_mul_f32_e64 v92, v92, -v84
	v_mul_f32_e64 v93, v93, -v85
	v_sub_f32_e32 v102, 1.0, v86
	v_sub_f32_e32 v103, 1.0, v87
	v_sub_f32_e32 v104, 1.0, v88
	v_sub_f32_e32 v105, 1.0, v89
	v_cmp_lt_f32_e32 vcc, s18, v82
	s_nop 1
	v_cndmask_b32_e32 v90, v102, v90, vcc
	v_cmp_lt_f32_e32 vcc, s18, v83
	s_nop 1
	v_cndmask_b32_e32 v91, v103, v91, vcc
	v_cmp_lt_f32_e32 vcc, s18, v84
	s_nop 1
	v_cndmask_b32_e32 v92, v104, v92, vcc
	v_cmp_lt_f32_e32 vcc, s18, v85
	s_nop 1
	v_cndmask_b32_e32 v93, v105, v93, vcc
	v_add_f32_e32 v106, v82, v82
	v_add_f32_e32 v107, v83, v83
	v_add_f32_e32 v108, v84, v84
	v_add_f32_e32 v109, v85, v85
	v_fmamk_f32 v98, v106, 0x3d2aaaab, v252
	v_fmamk_f32 v99, v107, 0x3d2aaaab, v252
	v_fmamk_f32 v100, v108, 0x3d2aaaab, v252
	v_fmamk_f32 v101, v109, 0x3d2aaaab, v252
	v_fma_f32 v98, v106, v98, 0.5
	v_fma_f32 v99, v107, v99, 0.5
	v_fma_f32 v100, v108, v100, 0.5
	v_fma_f32 v101, v109, v101, 0.5
	v_fma_f32 v98, v106, v98, 1.0
	v_fma_f32 v99, v107, v99, 1.0
	v_fma_f32 v100, v108, v100, 1.0
	v_fma_f32 v101, v109, v101, 1.0
	v_mul_f32_e64 v98, v98, -v106
	v_mul_f32_e64 v99, v99, -v107
	v_mul_f32_e64 v100, v100, -v108
	v_mul_f32_e64 v101, v101, -v109
	v_fma_f32 v102, -v86, v86, 1.0
	v_fma_f32 v103, -v87, v87, 1.0
	v_fma_f32 v104, -v88, v88, 1.0
	v_fma_f32 v105, -v89, v89, 1.0
	v_cmp_lt_f32_e32 vcc, s19, v106
	s_nop 1
	v_cndmask_b32_e32 v98, v102, v98, vcc
	v_cmp_lt_f32_e32 vcc, s19, v107
	s_nop 1
	v_cndmask_b32_e32 v99, v103, v99, vcc
	v_cmp_lt_f32_e32 vcc, s19, v108
	s_nop 1
	v_cndmask_b32_e32 v100, v104, v100, vcc
	v_cmp_lt_f32_e32 vcc, s19, v109
	s_nop 1
	v_cndmask_b32_e32 v101, v105, v101, vcc
	v_sqrt_f32_e32 v98, v98
	v_sqrt_f32_e32 v99, v99
	v_sqrt_f32_e32 v100, v100
	v_sqrt_f32_e32 v101, v101
	v_mul_f32_e32 v58, v58, v78
	v_mul_f32_e32 v59, v59, v79
	v_mul_f32_e32 v60, v60, v80
	v_mul_f32_e32 v61, v61, v81
	v_mul_f32_e32 v98, v98, v58
	v_mul_f32_e32 v99, v99, v59
	v_mul_f32_e32 v100, v100, v60
	v_mul_f32_e32 v101, v101, v61
	v_cvt_pk_bf16_f32 v248, v90, v98
	v_cvt_pk_bf16_f32 v249, v91, v99
	v_cvt_pk_bf16_f32 v250, v92, v100
	v_cvt_pk_bf16_f32 v251, v93, v101
	global_store_dwordx4 v130, v[248:251], s[78:79] offset:256
	s_add_i32 s2, s2, s94
	s_branch .Llg_task
.Llg_done:
.LBB0_1870:
	v_readlane_b32 s68, v255, 8
	s_movk_i32 s88, 0x7f
	s_mov_b32 s96, 0x19000
	s_mov_b32 s97, 0x50000
	v_readlane_b32 s89, v255, 19
	v_readlane_b32 s69, v255, 9
